# attention step tail: always-false alpha compare plus conditional branch on the common path replaced by an unconditional branch
# baseline (speedup 1.0000x reference)
; __device__ __forceinline__ void finishSM(f32x16& p0, f32x16& p1, float alpha, float& l_reg, bf16x8& pa0, bf16x8& pa1, bf16x8& pa2, bf16x8& pa3) {
; #pragma unroll
;   for (int r = 0; r < 16; ++r) p1[r] = __builtin_amdgcn_exp2f(p1[r]);
;   float ps = 0;
; #pragma unroll
;   for (int r = 0; r < 16; ++r) ps += p0[r];
; #pragma unroll
;   for (int r = 0; r < 16; ++r) ps += p1[r];
;   { auto rr = __builtin_amdgcn_permlane32_swap(__float_as_uint(ps), __float_as_uint(ps), false, false);
;     ps = __uint_as_float(rr[0]) + __uint_as_float(rr[1]); }
;   l_reg = l_reg * alpha + ps;
; template <bool MLA>
; __device__ __forceinline__ void qkt(f32x16& p0, f32x16& p1, const char* Ks, const char* KRs, const bf16x8* qr, const char* qrl, const f32x16& negm, int r32, int hi) {
; #pragma unroll
;   for (int d0 = 0; d0 < 8; ++d0) { int cb = (d0 * 16 + hi * 8) * 2;
;     bf16x8 b0 = *reinterpret_cast<const bf16x8*>(Ks + KSWZ(r32, cb));
;     bf16x8 b1 = *reinterpret_cast<const bf16x8*>(Ks + KSWZ(32 + r32, cb));
;     if (d0 == 0) { p0 = __builtin_amdgcn_mfma_f32_32x32x16_bf16(b0, qr[0], negm, 0, 0, 0); p1 = __builtin_amdgcn_mfma_f32_32x32x16_bf16(b1, qr[0], negm, 0, 0, 0); }
;     else { p0 = __builtin_amdgcn_mfma_f32_32x32x16_bf16(b0, qr[d0], p0, 0, 0, 0); p1 = __builtin_amdgcn_mfma_f32_32x32x16_bf16(b1, qr[d0], p1, 0, 0, 0); } }
;   if constexpr (MLA) {
; #pragma unroll
;     for (int d0 = 0; d0 < 4; ++d0) { int ch = d0 * 2 + hi;
;       bf16x8 b0 = *reinterpret_cast<const bf16x8*>(KRs + KRSWZ(r32, ch));
;       bf16x8 b1 = *reinterpret_cast<const bf16x8*>(KRs + KRSWZ(32 + r32, ch));
;       const bf16x8 qq = *reinterpret_cast<const bf16x8*>(qrl + d0 * 1024);
;       p0 = __builtin_amdgcn_mfma_f32_32x32x16_bf16(b0, qq, p0, 0, 0, 0);
;       p1 = __builtin_amdgcn_mfma_f32_32x32x16_bf16(b1, qq, p1, 0, 0, 0); }
;   }
; }
.LBB0_101:
	s_mov_b32 s10, s24
	s_mov_b32 s24, s35
	s_lshl_b32 s2, s25, 14
	s_add_i32 s27, s2, 0
	s_add_i32 s32, s27, s15
	s_lshl_b32 s30, s25, 13
	s_lshl_b32 s11, s10, 14
	s_add_i32 s3, s11, 0
	v_add_u32_e32 v0, s3, v210
	ds_read_b128 v[234:237], v0 offset:57344
	ds_read_b128 v[98:101], v0 offset:49152
	v_add_u32_e32 v0, s3, v209
	s_lshl_b32 s2, s10, 13
	s_add_i32 s2, s2, 0
	s_add_i32 s2, s2, 0x18000
	s_add_u32 vcc_lo, s28, s46
	s_addc_u32 vcc_hi, s29, s47
	s_add_i32 m0, s32, 0xc000
	v_lshl_add_u64 v[250:251], v[172:173], 0, vcc
	global_load_lds_dwordx4 v[250:251], off
	v_exp_f32_e32 v213, v82
	v_add_f32_e32 v212, 0, v227
	v_add_f32_e32 v212, v229, v212
	s_waitcnt lgkmcnt(0)
	v_mfma_f32_32x32x16_bf16 v[114:129], v[98:101], v[158:161], v[66:81]
	v_exp_f32_e32 v246, v83
	v_add_f32_e32 v212, v225, v212
	v_add_f32_e32 v212, v228, v212
	s_lshl_b32 s31, s35, 14
	v_mfma_f32_32x32x16_bf16 v[98:113], v[234:237], v[158:161], v[66:81]
	ds_read_b128 v[234:237], v0 offset:57344
	ds_read_b128 v[238:241], v0 offset:49152
	v_add_u32_e32 v0, s3, v208
	s_add_u32 vcc_lo, s28, 0x4380100
	s_addc_u32 vcc_hi, s29, 0
	s_mov_b32 m0, s32
	v_lshl_add_u64 v[250:251], v[170:171], 0, vcc
	global_load_lds_dwordx4 v[250:251], off
	v_exp_f32_e32 v247, v84
	v_add_f32_e32 v212, v224, v212
	v_add_f32_e32 v212, v226, v212
	s_waitcnt lgkmcnt(0)
	v_mfma_f32_32x32x16_bf16 v[114:129], v[238:241], v[154:157], v[114:129]
	v_exp_f32_e32 v249, v85
	v_add_f32_e32 v212, v222, v212
	v_add_f32_e32 v212, v223, v212
	v_mfma_f32_32x32x16_bf16 v[98:113], v[234:237], v[154:157], v[98:113]
	ds_read_b128 v[234:237], v0 offset:57344
	ds_read_b128 v[238:241], v0 offset:49152
	v_add_u32_e32 v0, s3, v207
	s_add_u32 vcc_lo, s28, s46
	s_addc_u32 vcc_hi, s29, s47
	s_add_i32 m0, s32, 0xc400
	v_lshl_add_u64 v[250:251], v[174:175], 0, vcc
	global_load_lds_dwordx4 v[250:251], off
	v_exp_f32_e32 v252, v86
	v_add_f32_e32 v212, v219, v212
	v_add_f32_e32 v212, v221, v212
	s_waitcnt lgkmcnt(0)
	v_mfma_f32_32x32x16_bf16 v[114:129], v[238:241], v[150:153], v[114:129]
	v_exp_f32_e32 v253, v87
	v_add_f32_e32 v212, v218, v212
	v_add_f32_e32 v212, v220, v212
	v_mfma_f32_32x32x16_bf16 v[98:113], v[234:237], v[150:153], v[98:113]
	ds_read_b128 v[234:237], v0 offset:57344
	ds_read_b128 v[238:241], v0 offset:49152
	v_add_u32_e32 v0, s3, v206
	s_add_u32 vcc_lo, s28, 0x4380180
	s_addc_u32 vcc_hi, s29, 0
	s_add_i32 m0, s32, 0x400
	v_lshl_add_u64 v[250:251], v[170:171], 0, vcc
	global_load_lds_dwordx4 v[250:251], off
	v_exp_f32_e32 v254, v88
	v_add_f32_e32 v212, v215, v212
	v_add_f32_e32 v212, v217, v212
	s_waitcnt lgkmcnt(0)
	v_mfma_f32_32x32x16_bf16 v[114:129], v[238:241], v[146:149], v[114:129]
	v_exp_f32_e32 v255, v89
	v_add_f32_e32 v212, v214, v212
	v_add_f32_e32 v212, v216, v212
	v_mfma_f32_32x32x16_bf16 v[98:113], v[234:237], v[146:149], v[98:113]
	ds_read_b128 v[234:237], v0 offset:57344
	ds_read_b128 v[238:241], v0 offset:49152
	v_add_u32_e32 v0, s3, v205
	s_add_u32 vcc_lo, s28, 0x2e340600
	s_addc_u32 vcc_hi, s29, 0
	s_add_i32 m0, s23, s30
	v_lshl_add_u64 v[250:251], v[168:169], 0, vcc
	global_load_lds_dwordx4 v[250:251], off
	v_cvt_pk_bf16_f32 v82, v227, v229
	v_exp_f32_e32 v90, v90
	v_cvt_pk_bf16_f32 v83, v225, v228
	s_waitcnt lgkmcnt(0)
	v_mfma_f32_32x32x16_bf16 v[114:129], v[238:241], v[142:145], v[114:129]
	v_exp_f32_e32 v91, v91
	v_cvt_pk_bf16_f32 v84, v224, v226
	v_exp_f32_e32 v92, v92
	v_mfma_f32_32x32x16_bf16 v[98:113], v[234:237], v[142:145], v[98:113]
	ds_read_b128 v[234:237], v0 offset:57344
	ds_read_b128 v[238:241], v0 offset:49152
	v_add_u32_e32 v0, s3, v204
	v_cvt_pk_bf16_f32 v85, v222, v223
	v_exp_f32_e32 v93, v93
	v_cvt_pk_bf16_f32 v86, v219, v221
	s_waitcnt lgkmcnt(0)
	v_mfma_f32_32x32x16_bf16 v[114:129], v[238:241], v[138:141], v[114:129]
	v_exp_f32_e32 v94, v94
	v_cvt_pk_bf16_f32 v87, v218, v220
	v_exp_f32_e32 v95, v95
	v_mfma_f32_32x32x16_bf16 v[98:113], v[234:237], v[138:141], v[98:113]
	ds_read_b128 v[234:237], v0 offset:57344
	ds_read_b128 v[238:241], v0 offset:49152
	v_add_u32_e32 v0, s3, v203
	v_cvt_pk_bf16_f32 v88, v215, v217
	v_exp_f32_e32 v96, v96
	v_cvt_pk_bf16_f32 v89, v214, v216
	s_waitcnt lgkmcnt(0)
	v_mfma_f32_32x32x16_bf16 v[114:129], v[238:241], v[134:137], v[114:129]
	v_exp_f32_e32 v97, v97
	v_add_f32_e32 v212, v213, v212
	v_add_f32_e32 v212, v246, v212
	v_mfma_f32_32x32x16_bf16 v[98:113], v[234:237], v[134:137], v[98:113]
	ds_read_b128 v[234:237], v0 offset:57344
	ds_read_b128 v[238:241], v0 offset:49152
	v_add_u32_e32 v0, s2, v200
	v_add_f32_e32 v212, v247, v212
	v_add_f32_e32 v212, v249, v212
	v_add_f32_e32 v212, v252, v212
	s_waitcnt lgkmcnt(0)
	v_mfma_f32_32x32x16_bf16 v[114:129], v[238:241], v[130:133], v[114:129]
	v_add_f32_e32 v212, v253, v212
	v_add_f32_e32 v212, v254, v212
	v_add_f32_e32 v212, v255, v212
	v_mfma_f32_32x32x16_bf16 v[98:113], v[234:237], v[130:133], v[98:113]
	ds_read_b128 v[234:237], v0
	ds_read_b128 v[238:241], v0 offset:4096
	ds_read_b128 v[242:245], v198
	v_add_u32_e32 v0, s2, v201
	v_add_f32_e32 v212, v90, v212
	v_add_f32_e32 v212, v91, v212
	s_waitcnt lgkmcnt(0)
	v_mfma_f32_32x32x16_bf16 v[114:129], v[234:237], v[242:245], v[114:129]
	v_add_f32_e32 v212, v92, v212
	v_add_f32_e32 v212, v93, v212
	v_mfma_f32_32x32x16_bf16 v[98:113], v[238:241], v[242:245], v[98:113]
	ds_read_b128 v[234:237], v0
	ds_read_b128 v[238:241], v0 offset:4096
	ds_read_b128 v[242:245], v198 offset:1024
	v_add_u32_e32 v0, s2, v199
	v_add_f32_e32 v212, v94, v212
	v_add_f32_e32 v212, v95, v212
	s_waitcnt lgkmcnt(0)
; #define SBAR() __builtin_amdgcn_sched_barrier(0)
; __device__ __forceinline__ float max3f(float a, float b, float c) { return __builtin_fmaxf(__builtin_fmaxf(a, b), c); }
; template <bool FIRST, bool MLA>
; __device__ __forceinline__ void partialSM(f32x16& p0, f32x16& p1, f32x16& negm, float& m_reg, float& alpha) {
;   float a = max3f(p0[0], p0[1], p1[0]), b = max3f(p0[2], p0[3], p1[1]); a = max3f(a, p1[2], p1[3]);
; #pragma unroll
;   for (int r = 4; r < 16; r += 4) { a = max3f(a, p0[r], p0[r + 1]); b = max3f(b, p0[r + 2], p0[r + 3]); a = max3f(a, p1[r], p1[r + 1]); b = max3f(b, p1[r + 2], p1[r + 3]); }
;   float pmax = fmaxf(a, b);
;   { auto rr = __builtin_amdgcn_permlane32_swap(__float_as_uint(pmax), __float_as_uint(pmax), false, false);
;     pmax = fmaxf(__uint_as_float(rr[0]), __uint_as_float(rr[1])); }
;   alpha = 1.f;
;   if constexpr (MLA) {
;     if (FIRST) m_reg = pmax;
;     else if (!__builtin_expect(__all(pmax - m_reg <= THR2), 1)) { const float mn = fmaxf(m_reg, pmax); alpha = __builtin_amdgcn_exp2f(m_reg - mn); m_reg = mn; }
; #pragma unroll
;     for (int r = 0; r < 16; ++r) { p0[r] -= m_reg; p1[r] -= m_reg; }
;   } else
;   if (FIRST || __builtin_expect(__any(pmax > THR2), 0)) {
; template <int D0> __device__ __forceinline__ void pv_one(f32x16& od, int vb, bf16x8 pa0, bf16x8 pa1, bf16x8 pa2, bf16x8 pa3) {
;   const s16x4 l0 = tr_read<v_rd_off(D0, 0, 0)>(vb), h0 = tr_read<v_rd_off(D0, 0, 1)>(vb), l1 = tr_read<v_rd_off(D0, 1, 0)>(vb), h1 = tr_read<v_rd_off(D0, 1, 1)>(vb);
;   const s16x4 l2 = tr_read<v_rd_off(D0, 2, 0)>(vb), h2 = tr_read<v_rd_off(D0, 2, 1)>(vb), l3 = tr_read<v_rd_off(D0, 3, 0)>(vb), h3 = tr_read<v_rd_off(D0, 3, 1)>(vb);
;   asm volatile("s_waitcnt lgkmcnt(0)" ::: "memory"); SBAR();
;     ...
;   od = __builtin_amdgcn_mfma_f32_32x32x16_bf16(pa0, PK(l0, h0), od, 0, 0, 0);
;   od = __builtin_amdgcn_mfma_f32_32x32x16_bf16(pa1, PK(l1, h1), od, 0, 0, 0);
;   od = __builtin_amdgcn_mfma_f32_32x32x16_bf16(pa2, PK(l2, h2), od, 0, 0, 0);
;   od = __builtin_amdgcn_mfma_f32_32x32x16_bf16(pa3, PK(l3, h3), od, 0, 0, 0);
;     ...
; }
; __device__ __forceinline__ void pv_d0(f32x16* o, int vb, bf16x8 pa0, bf16x8 pa1, bf16x8 pa2, bf16x8 pa3) {
;   pv_one<0>(o[0], vb, pa0, pa1, pa2, pa3); pv_one<1>(o[1], vb, pa0, pa1, pa2, pa3); pv_one<2>(o[2], vb, pa0, pa1, pa2, pa3); pv_one<3>(o[3], vb, pa0, pa1, pa2, pa3);
	v_mfma_f32_32x32x16_bf16 v[114:129], v[234:237], v[242:245], v[114:129]
	v_add_f32_e32 v212, v96, v212
	v_add_f32_e32 v212, v97, v212
	v_mfma_f32_32x32x16_bf16 v[98:113], v[238:241], v[242:245], v[98:113]
	ds_read_b128 v[234:237], v0
	ds_read_b128 v[238:241], v0 offset:4096
	ds_read_b128 v[242:245], v198 offset:2048
	v_add_u32_e32 v0, s2, v202
	v_cvt_pk_bf16_f32 v97, v96, v97
	v_cvt_pk_bf16_f32 v96, v94, v95
	s_waitcnt lgkmcnt(0)
	v_mfma_f32_32x32x16_bf16 v[114:129], v[234:237], v[242:245], v[114:129]
	v_cvt_pk_bf16_f32 v95, v92, v93
	v_cvt_pk_bf16_f32 v94, v90, v91
	v_mfma_f32_32x32x16_bf16 v[98:113], v[238:241], v[242:245], v[98:113]
	ds_read_b128 v[234:237], v0
	ds_read_b128 v[238:241], v0 offset:4096
	ds_read_b128 v[242:245], v198 offset:3072
	v_cvt_pk_bf16_f32 v90, v213, v246
	v_cvt_pk_bf16_f32 v91, v247, v249
	s_waitcnt lgkmcnt(0)
	v_mfma_f32_32x32x16_bf16 v[114:129], v[234:237], v[242:245], v[114:129]
	v_cvt_pk_bf16_f32 v92, v252, v253
	v_cvt_pk_bf16_f32 v93, v254, v255
	v_mfma_f32_32x32x16_bf16 v[98:113], v[238:241], v[242:245], v[98:113]
	v_add_u32_e32 v213, s31, v197
	ds_read_b64_tr_b16 v[214:215], v213 offset:0
	ds_read_b64_tr_b16 v[216:217], v213 offset:0x800
	ds_read_b64_tr_b16 v[218:219], v213 offset:0x1000
	ds_read_b64_tr_b16 v[220:221], v213 offset:0x1800
	ds_read_b64_tr_b16 v[222:223], v213 offset:0x2000
	ds_read_b64_tr_b16 v[224:225], v213 offset:0x2800
	ds_read_b64_tr_b16 v[226:227], v213 offset:0x3000
	ds_read_b64_tr_b16 v[228:229], v213 offset:0x3800
	s_waitcnt lgkmcnt(0)
	v_mov_b32_e32 v0, v212
	s_nop 1
	v_permlane32_swap_b32_e32 v0, v212
	v_permlane32_swap_b32_e32 v82, v84
	v_permlane32_swap_b32_e32 v83, v85
	v_permlane32_swap_b32_e32 v86, v88
	v_permlane32_swap_b32_e32 v87, v89
	v_permlane32_swap_b32_e32 v90, v92
	v_permlane32_swap_b32_e32 v91, v93
	v_permlane32_swap_b32_e32 v94, v96
	v_permlane32_swap_b32_e32 v95, v97
	v_mfma_f32_32x32x16_bf16 v[50:65], v[82:85], v[214:217], v[50:65]
	ds_read_b64_tr_b16 v[214:215], v213 offset:0x200
	ds_read_b64_tr_b16 v[216:217], v213 offset:0xa00
	v_mfma_f32_32x32x16_bf16 v[50:65], v[86:89], v[218:221], v[50:65]
	ds_read_b64_tr_b16 v[218:219], v213 offset:0x1200
	ds_read_b64_tr_b16 v[220:221], v213 offset:0x1a00
	v_mfma_f32_32x32x16_bf16 v[50:65], v[90:93], v[222:225], v[50:65]
	ds_read_b64_tr_b16 v[222:223], v213 offset:0x2200
	ds_read_b64_tr_b16 v[224:225], v213 offset:0x2a00
	v_mfma_f32_32x32x16_bf16 v[50:65], v[94:97], v[226:229], v[50:65]
	ds_read_b64_tr_b16 v[226:227], v213 offset:0x3200
	ds_read_b64_tr_b16 v[228:229], v213 offset:0x3a00
	s_waitcnt lgkmcnt(6)
	v_mfma_f32_32x32x16_bf16 v[34:49], v[82:85], v[214:217], v[34:49]
	ds_read_b64_tr_b16 v[214:215], v213 offset:0x400
	ds_read_b64_tr_b16 v[216:217], v213 offset:0xc00
	s_waitcnt lgkmcnt(6)
	v_mfma_f32_32x32x16_bf16 v[34:49], v[86:89], v[218:221], v[34:49]
	ds_read_b64_tr_b16 v[218:219], v213 offset:0x1400
	ds_read_b64_tr_b16 v[220:221], v213 offset:0x1c00
	s_waitcnt lgkmcnt(6)
	v_mfma_f32_32x32x16_bf16 v[34:49], v[90:93], v[222:225], v[34:49]
	ds_read_b64_tr_b16 v[222:223], v213 offset:0x2400
	ds_read_b64_tr_b16 v[224:225], v213 offset:0x2c00
	s_waitcnt lgkmcnt(6)
	v_mfma_f32_32x32x16_bf16 v[34:49], v[94:97], v[226:229], v[34:49]
	ds_read_b64_tr_b16 v[226:227], v213 offset:0x3400
	ds_read_b64_tr_b16 v[228:229], v213 offset:0x3c00
	s_waitcnt lgkmcnt(6)
	v_mfma_f32_32x32x16_bf16 v[18:33], v[82:85], v[214:217], v[18:33]
	ds_read_b64_tr_b16 v[214:215], v213 offset:0x600
	ds_read_b64_tr_b16 v[216:217], v213 offset:0xe00
	s_waitcnt lgkmcnt(6)
	v_mfma_f32_32x32x16_bf16 v[18:33], v[86:89], v[218:221], v[18:33]
	ds_read_b64_tr_b16 v[218:219], v213 offset:0x1600
	ds_read_b64_tr_b16 v[220:221], v213 offset:0x1e00
	s_waitcnt lgkmcnt(6)
	v_mfma_f32_32x32x16_bf16 v[18:33], v[90:93], v[222:225], v[18:33]
	ds_read_b64_tr_b16 v[222:223], v213 offset:0x2600
	ds_read_b64_tr_b16 v[224:225], v213 offset:0x2e00
	s_waitcnt lgkmcnt(6)
	v_mfma_f32_32x32x16_bf16 v[18:33], v[94:97], v[226:229], v[18:33]
	ds_read_b64_tr_b16 v[226:227], v213 offset:0x3600
	ds_read_b64_tr_b16 v[228:229], v213 offset:0x3e00
	s_waitcnt lgkmcnt(6)
	v_mfma_f32_32x32x16_bf16 v[2:17], v[82:85], v[214:217], v[2:17]
	v_max_f32_e32 v82, v115, v115
	v_max_f32_e32 v83, v114, v114
	v_max_f32_e32 v82, v83, v82
	v_max3_f32 v83, v116, v117, v99
	v_max3_f32 v82, v82, v98, v100
	v_max3_f32 v82, v82, v101, v118
	v_max3_f32 v83, v83, v120, v121
	s_waitcnt lgkmcnt(4)
	v_mfma_f32_32x32x16_bf16 v[2:17], v[86:89], v[218:221], v[2:17]
	v_max3_f32 v82, v82, v119, v102
	v_max3_f32 v83, v83, v104, v105
	v_max3_f32 v82, v82, v103, v122
	v_max3_f32 v83, v83, v124, v125
	v_max3_f32 v82, v82, v123, v106
	v_max3_f32 v83, v83, v108, v109
	v_max3_f32 v82, v82, v107, v126
	s_waitcnt lgkmcnt(2)
	v_mfma_f32_32x32x16_bf16 v[2:17], v[90:93], v[222:225], v[2:17]
	v_max3_f32 v83, v83, v128, v129
	v_max3_f32 v82, v82, v127, v110
	v_max3_f32 v83, v83, v112, v113
	v_max3_f32 v82, v82, v111, v83
	v_mov_b32_e32 v83, v82
	s_nop 1
	v_permlane32_swap_b32_e32 v82, v83
	s_waitcnt lgkmcnt(0)
	v_mfma_f32_32x32x16_bf16 v[2:17], v[94:97], v[226:229], v[2:17]
	v_max_f32_e32 v83, v83, v83
	v_max_f32_e32 v82, v82, v82
	v_max_f32_e32 v82, v82, v83
	v_cmp_lt_f32_e32 vcc, s40, v82
	s_cbranch_vccnz .LBB0_113
	v_mov_b32_e32 v213, 1.0
	s_branch .LBB0_106

; template <bool FIRST, bool MLA>
; __device__ __forceinline__ void partialSM(f32x16& p0, f32x16& p1, f32x16& negm, float& m_reg, float& alpha) {
;     ...
;   for (int r = 0; r < 16; ++r) p0[r] = __builtin_amdgcn_exp2f(p0[r]);
; }
; __device__ __forceinline__ void finishSM(f32x16& p0, f32x16& p1, float alpha, float& l_reg, bf16x8& pa0, bf16x8& pa1, bf16x8& pa2, bf16x8& pa3) {
; #pragma unroll
;   for (int r = 0; r < 16; ++r) p1[r] = __builtin_amdgcn_exp2f(p1[r]);
;   float ps = 0;
; #pragma unroll
;   for (int r = 0; r < 16; ++r) ps += p0[r];
; #pragma unroll
;   for (int r = 0; r < 16; ++r) ps += p1[r];
;   { auto rr = __builtin_amdgcn_permlane32_swap(__float_as_uint(ps), __float_as_uint(ps), false, false);
;     ps = __uint_as_float(rr[0]) + __uint_as_float(rr[1]); }
;   l_reg = l_reg * alpha + ps;
; template <bool MLA>
; __device__ __forceinline__ void qkt(f32x16& p0, f32x16& p1, const char* Ks, const char* KRs, const bf16x8* qr, const char* qrl, const f32x16& negm, int r32, int hi) {
; #pragma unroll
;   for (int d0 = 0; d0 < 8; ++d0) { int cb = (d0 * 16 + hi * 8) * 2;
;     bf16x8 b0 = *reinterpret_cast<const bf16x8*>(Ks + KSWZ(r32, cb));
;     bf16x8 b1 = *reinterpret_cast<const bf16x8*>(Ks + KSWZ(32 + r32, cb));
;     if (d0 == 0) { p0 = __builtin_amdgcn_mfma_f32_32x32x16_bf16(b0, qr[0], negm, 0, 0, 0); p1 = __builtin_amdgcn_mfma_f32_32x32x16_bf16(b1, qr[0], negm, 0, 0, 0); }
;     else { p0 = __builtin_amdgcn_mfma_f32_32x32x16_bf16(b0, qr[d0], p0, 0, 0, 0); p1 = __builtin_amdgcn_mfma_f32_32x32x16_bf16(b1, qr[d0], p1, 0, 0, 0); } }
;   if constexpr (MLA) {
; #pragma unroll
;     for (int d0 = 0; d0 < 4; ++d0) { int ch = d0 * 2 + hi;
;       bf16x8 b0 = *reinterpret_cast<const bf16x8*>(KRs + KRSWZ(r32, ch));
;       bf16x8 b1 = *reinterpret_cast<const bf16x8*>(KRs + KRSWZ(32 + r32, ch));
;       const bf16x8 qq = *reinterpret_cast<const bf16x8*>(qrl + d0 * 1024);
;       p0 = __builtin_amdgcn_mfma_f32_32x32x16_bf16(b0, qq, p0, 0, 0, 0);
;       p1 = __builtin_amdgcn_mfma_f32_32x32x16_bf16(b1, qq, p1, 0, 0, 0); }
;   }
; }
.LBB0_106:
	s_waitcnt vmcnt(0)
	v_exp_f32_e32 v218, v114
	v_exp_f32_e32 v219, v115
	v_exp_f32_e32 v220, v116
	v_exp_f32_e32 v221, v117
	v_exp_f32_e32 v222, v118
	v_exp_f32_e32 v223, v119
	v_exp_f32_e32 v224, v120
	v_exp_f32_e32 v225, v121
	v_exp_f32_e32 v226, v122
	v_exp_f32_e32 v227, v123
	v_exp_f32_e32 v228, v124
	v_exp_f32_e32 v229, v125
	v_exp_f32_e32 v234, v126
	v_exp_f32_e32 v235, v127
	v_exp_f32_e32 v236, v128
	v_exp_f32_e32 v237, v129
	s_waitcnt vmcnt(0)
	s_barrier
	s_add_i32 s31, s19, s31
	v_add_u32_e32 v82, s27, v210
	ds_read_b128 v[176:179], v82 offset:57344
	ds_read_b128 v[82:85], v82 offset:49152
	v_add_u32_e32 v180, s27, v209
	s_add_i32 s2, s30, 0
	s_add_i32 s2, s2, 0x18000
	s_add_u32 vcc_lo, s28, s48
	s_addc_u32 vcc_hi, s29, s49
	s_add_i32 m0, s31, 0xc000
	v_lshl_add_u64 v[250:251], v[172:173], 0, vcc
	global_load_lds_dwordx4 v[250:251], off
	v_exp_f32_e32 v238, v100
	v_add_f32_e32 v255, 0, v218
	v_add_f32_e32 v255, v219, v255
	s_waitcnt lgkmcnt(0)
	v_mfma_f32_32x32x16_bf16 v[114:129], v[82:85], v[158:161], v[66:81]
	v_exp_f32_e32 v239, v101
	v_add_f32_e32 v255, v220, v255
	v_add_f32_e32 v255, v221, v255
	v_mfma_f32_32x32x16_bf16 v[82:97], v[176:179], v[158:161], v[66:81]
	ds_read_b128 v[176:179], v180 offset:57344
	ds_read_b128 v[180:183], v180 offset:49152
	s_add_u32 vcc_lo, s28, 0x43c0100
	s_addc_u32 vcc_hi, s29, 0
	s_mov_b32 m0, s31
	v_lshl_add_u64 v[250:251], v[170:171], 0, vcc
	global_load_lds_dwordx4 v[250:251], off
	v_exp_f32_e32 v246, v102
	v_add_f32_e32 v255, v222, v255
	v_add_f32_e32 v255, v223, v255
	s_waitcnt lgkmcnt(0)
	v_mfma_f32_32x32x16_bf16 v[114:129], v[180:183], v[154:157], v[114:129]
	v_exp_f32_e32 v247, v103
	v_add_f32_e32 v255, v224, v255
	v_add_f32_e32 v255, v225, v255
	v_add_u32_e32 v180, s27, v208
	v_mfma_f32_32x32x16_bf16 v[82:97], v[176:179], v[154:157], v[82:97]
	ds_read_b128 v[176:179], v180 offset:57344
	ds_read_b128 v[180:183], v180 offset:49152
	s_add_u32 vcc_lo, s28, s48
	s_addc_u32 vcc_hi, s29, s49
	s_add_i32 m0, s31, 0xc400
	v_lshl_add_u64 v[250:251], v[174:175], 0, vcc
	global_load_lds_dwordx4 v[250:251], off
	v_exp_f32_e32 v249, v104
	v_add_f32_e32 v255, v226, v255
	v_add_f32_e32 v255, v227, v255
	s_waitcnt lgkmcnt(0)
	v_mfma_f32_32x32x16_bf16 v[114:129], v[180:183], v[150:153], v[114:129]
	v_exp_f32_e32 v252, v105
	v_add_f32_e32 v255, v228, v255
	v_add_f32_e32 v255, v229, v255
	v_add_u32_e32 v180, s27, v207
	v_mfma_f32_32x32x16_bf16 v[82:97], v[176:179], v[150:153], v[82:97]
	ds_read_b128 v[176:179], v180 offset:57344
	ds_read_b128 v[180:183], v180 offset:49152
	s_add_u32 vcc_lo, s28, 0x43c0180
	s_addc_u32 vcc_hi, s29, 0
	s_add_i32 m0, s31, 0x400
	v_lshl_add_u64 v[250:251], v[170:171], 0, vcc
	global_load_lds_dwordx4 v[250:251], off
	v_exp_f32_e32 v253, v106
	v_add_f32_e32 v255, v234, v255
	v_add_f32_e32 v255, v235, v255
	s_waitcnt lgkmcnt(0)
	v_mfma_f32_32x32x16_bf16 v[114:129], v[180:183], v[146:149], v[114:129]
	v_exp_f32_e32 v254, v107
	v_add_f32_e32 v255, v236, v255
	v_add_f32_e32 v255, v237, v255
	v_add_u32_e32 v180, s27, v206
	v_mfma_f32_32x32x16_bf16 v[82:97], v[176:179], v[146:149], v[82:97]
	ds_read_b128 v[176:179], v180 offset:57344
	ds_read_b128 v[180:183], v180 offset:49152
	s_lshl_b32 s32, s24, 13
	s_add_u32 vcc_lo, s28, 0x2e360600
	s_addc_u32 vcc_hi, s29, 0
	s_add_i32 m0, s23, s32
	v_lshl_add_u64 v[250:251], v[168:169], 0, vcc
	global_load_lds_dwordx4 v[250:251], off
	v_cvt_pk_bf16_f32 v100, v218, v219
	v_exp_f32_e32 v98, v98
	s_waitcnt lgkmcnt(0)
	v_mfma_f32_32x32x16_bf16 v[114:129], v[180:183], v[142:145], v[114:129]
	v_cvt_pk_bf16_f32 v101, v220, v221
	v_exp_f32_e32 v99, v99
	v_add_u32_e32 v180, s27, v205
	v_mfma_f32_32x32x16_bf16 v[82:97], v[176:179], v[142:145], v[82:97]
	ds_read_b128 v[176:179], v180 offset:57344
	ds_read_b128 v[180:183], v180 offset:49152
	v_cvt_pk_bf16_f32 v102, v222, v223
	v_exp_f32_e32 v108, v108
	s_waitcnt lgkmcnt(0)
	v_mfma_f32_32x32x16_bf16 v[114:129], v[180:183], v[138:141], v[114:129]
	v_cvt_pk_bf16_f32 v103, v224, v225
	v_exp_f32_e32 v109, v109
	v_add_u32_e32 v180, s27, v204
	v_mfma_f32_32x32x16_bf16 v[82:97], v[176:179], v[138:141], v[82:97]
	ds_read_b128 v[176:179], v180 offset:57344
	ds_read_b128 v[180:183], v180 offset:49152
	v_cvt_pk_bf16_f32 v104, v226, v227
	v_exp_f32_e32 v110, v110
	s_waitcnt lgkmcnt(0)
	v_mfma_f32_32x32x16_bf16 v[114:129], v[180:183], v[134:137], v[114:129]
	v_cvt_pk_bf16_f32 v105, v228, v229
	v_exp_f32_e32 v111, v111
	v_add_u32_e32 v180, s27, v203
	v_mfma_f32_32x32x16_bf16 v[82:97], v[176:179], v[134:137], v[82:97]
	ds_read_b128 v[176:179], v180 offset:57344
	ds_read_b128 v[180:183], v180 offset:49152
	v_cvt_pk_bf16_f32 v106, v234, v235
	v_exp_f32_e32 v112, v112
	s_waitcnt lgkmcnt(0)
	v_mfma_f32_32x32x16_bf16 v[114:129], v[180:183], v[130:133], v[114:129]
	v_cvt_pk_bf16_f32 v107, v236, v237
	v_exp_f32_e32 v113, v113
	v_add_u32_e32 v180, s2, v200
	v_mfma_f32_32x32x16_bf16 v[82:97], v[176:179], v[130:133], v[82:97]
	ds_read_b128 v[176:179], v180
	ds_read_b128 v[180:183], v180 offset:4096
	ds_read_b128 v[214:217], v198
	v_add_f32_e32 v255, v98, v255
	v_add_f32_e32 v255, v99, v255
	s_waitcnt lgkmcnt(0)
	v_mfma_f32_32x32x16_bf16 v[114:129], v[176:179], v[214:217], v[114:129]
	v_add_f32_e32 v255, v238, v255
	v_add_f32_e32 v255, v239, v255
	v_mfma_f32_32x32x16_bf16 v[82:97], v[180:183], v[214:217], v[82:97]
	v_add_u32_e32 v180, s2, v201
	ds_read_b128 v[176:179], v180
	ds_read_b128 v[180:183], v180 offset:4096
	ds_read_b128 v[214:217], v198 offset:1024
	v_add_f32_e32 v255, v246, v255
	v_add_f32_e32 v255, v247, v255
	s_waitcnt lgkmcnt(0)
; #define SBAR() __builtin_amdgcn_sched_barrier(0)
; __device__ __forceinline__ float max3f(float a, float b, float c) { return __builtin_fmaxf(__builtin_fmaxf(a, b), c); }
; template <bool FIRST, bool MLA>
; __device__ __forceinline__ void partialSM(f32x16& p0, f32x16& p1, f32x16& negm, float& m_reg, float& alpha) {
;   float a = max3f(p0[0], p0[1], p1[0]), b = max3f(p0[2], p0[3], p1[1]); a = max3f(a, p1[2], p1[3]);
; #pragma unroll
;   for (int r = 4; r < 16; r += 4) { a = max3f(a, p0[r], p0[r + 1]); b = max3f(b, p0[r + 2], p0[r + 3]); a = max3f(a, p1[r], p1[r + 1]); b = max3f(b, p1[r + 2], p1[r + 3]); }
;   float pmax = fmaxf(a, b);
;   { auto rr = __builtin_amdgcn_permlane32_swap(__float_as_uint(pmax), __float_as_uint(pmax), false, false);
;     pmax = fmaxf(__uint_as_float(rr[0]), __uint_as_float(rr[1])); }
;   alpha = 1.f;
;   if constexpr (MLA) {
;     if (FIRST) m_reg = pmax;
;     else if (!__builtin_expect(__all(pmax - m_reg <= THR2), 1)) { const float mn = fmaxf(m_reg, pmax); alpha = __builtin_amdgcn_exp2f(m_reg - mn); m_reg = mn; }
; #pragma unroll
;     for (int r = 0; r < 16; ++r) { p0[r] -= m_reg; p1[r] -= m_reg; }
;   } else
;   if (FIRST || __builtin_expect(__any(pmax > THR2), 0)) {
; template <int D0> __device__ __forceinline__ void pv_one(f32x16& od, int vb, bf16x8 pa0, bf16x8 pa1, bf16x8 pa2, bf16x8 pa3) {
;   const s16x4 l0 = tr_read<v_rd_off(D0, 0, 0)>(vb), h0 = tr_read<v_rd_off(D0, 0, 1)>(vb), l1 = tr_read<v_rd_off(D0, 1, 0)>(vb), h1 = tr_read<v_rd_off(D0, 1, 1)>(vb);
;   const s16x4 l2 = tr_read<v_rd_off(D0, 2, 0)>(vb), h2 = tr_read<v_rd_off(D0, 2, 1)>(vb), l3 = tr_read<v_rd_off(D0, 3, 0)>(vb), h3 = tr_read<v_rd_off(D0, 3, 1)>(vb);
;   asm volatile("s_waitcnt lgkmcnt(0)" ::: "memory"); SBAR();
;     ...
;   od = __builtin_amdgcn_mfma_f32_32x32x16_bf16(pa0, PK(l0, h0), od, 0, 0, 0);
;   od = __builtin_amdgcn_mfma_f32_32x32x16_bf16(pa1, PK(l1, h1), od, 0, 0, 0);
;   od = __builtin_amdgcn_mfma_f32_32x32x16_bf16(pa2, PK(l2, h2), od, 0, 0, 0);
;   od = __builtin_amdgcn_mfma_f32_32x32x16_bf16(pa3, PK(l3, h3), od, 0, 0, 0);
;     ...
; }
; __device__ __forceinline__ void pv_d0(f32x16* o, int vb, bf16x8 pa0, bf16x8 pa1, bf16x8 pa2, bf16x8 pa3) {
;   pv_one<0>(o[0], vb, pa0, pa1, pa2, pa3); pv_one<1>(o[1], vb, pa0, pa1, pa2, pa3); pv_one<2>(o[2], vb, pa0, pa1, pa2, pa3); pv_one<3>(o[3], vb, pa0, pa1, pa2, pa3);
	v_mfma_f32_32x32x16_bf16 v[114:129], v[176:179], v[214:217], v[114:129]
	v_add_f32_e32 v255, v249, v255
	v_add_f32_e32 v255, v252, v255
	v_mfma_f32_32x32x16_bf16 v[82:97], v[180:183], v[214:217], v[82:97]
	v_add_u32_e32 v180, s2, v199
	ds_read_b128 v[176:179], v180
	ds_read_b128 v[180:183], v180 offset:4096
	ds_read_b128 v[214:217], v198 offset:2048
	v_add_f32_e32 v255, v253, v255
	v_add_f32_e32 v255, v254, v255
	s_waitcnt lgkmcnt(0)
	v_mfma_f32_32x32x16_bf16 v[114:129], v[176:179], v[214:217], v[114:129]
	v_add_f32_e32 v255, v108, v255
	v_add_f32_e32 v255, v109, v255
	v_mfma_f32_32x32x16_bf16 v[82:97], v[180:183], v[214:217], v[82:97]
	v_add_u32_e32 v180, s2, v202
	ds_read_b128 v[176:179], v180
	ds_read_b128 v[180:183], v180 offset:4096
	ds_read_b128 v[214:217], v198 offset:3072
	v_add_f32_e32 v255, v110, v255
	v_add_f32_e32 v255, v111, v255
	s_waitcnt lgkmcnt(0)
	v_mfma_f32_32x32x16_bf16 v[114:129], v[176:179], v[214:217], v[114:129]
	v_add_f32_e32 v255, v112, v255
	v_add_f32_e32 v255, v113, v255
	v_mfma_f32_32x32x16_bf16 v[82:97], v[180:183], v[214:217], v[82:97]
	v_cvt_pk_bf16_f32 v176, v253, v254
	v_cvt_pk_bf16_f32 v177, v108, v109
	v_cvt_pk_bf16_f32 v178, v110, v111
	v_cvt_pk_bf16_f32 v179, v112, v113
	v_cvt_pk_bf16_f32 v108, v98, v99
	v_cvt_pk_bf16_f32 v109, v238, v239
	v_cvt_pk_bf16_f32 v110, v246, v247
	v_cvt_pk_bf16_f32 v111, v249, v252
	v_mov_b32_e32 v98, v255
	v_add_u32_e32 v112, s11, v197
	ds_read_b64_tr_b16 v[180:181], v112 offset:0
	ds_read_b64_tr_b16 v[182:183], v112 offset:0x800
	ds_read_b64_tr_b16 v[214:215], v112 offset:0x1000
	ds_read_b64_tr_b16 v[216:217], v112 offset:0x1800
	ds_read_b64_tr_b16 v[218:219], v112 offset:0x2000
	ds_read_b64_tr_b16 v[220:221], v112 offset:0x2800
	ds_read_b64_tr_b16 v[222:223], v112 offset:0x3000
	ds_read_b64_tr_b16 v[224:225], v112 offset:0x3800
	s_waitcnt lgkmcnt(0)
	v_mov_b32_e32 v99, v98
	s_nop 1
	v_permlane32_swap_b32_e32 v98, v99
	v_permlane32_swap_b32_e32 v100, v102
	v_permlane32_swap_b32_e32 v176, v178
	v_permlane32_swap_b32_e32 v101, v103
	v_permlane32_swap_b32_e32 v104, v106
	v_permlane32_swap_b32_e32 v105, v107
	v_permlane32_swap_b32_e32 v108, v110
	v_permlane32_swap_b32_e32 v109, v111
	v_permlane32_swap_b32_e32 v177, v179
	v_mfma_f32_32x32x16_bf16 v[50:65], v[100:103], v[180:183], v[50:65]
	ds_read_b64_tr_b16 v[180:181], v112 offset:0x200
	ds_read_b64_tr_b16 v[182:183], v112 offset:0xa00
	v_mfma_f32_32x32x16_bf16 v[50:65], v[104:107], v[214:217], v[50:65]
	ds_read_b64_tr_b16 v[214:215], v112 offset:0x1200
	ds_read_b64_tr_b16 v[216:217], v112 offset:0x1a00
	v_mfma_f32_32x32x16_bf16 v[50:65], v[108:111], v[218:221], v[50:65]
	ds_read_b64_tr_b16 v[218:219], v112 offset:0x2200
	ds_read_b64_tr_b16 v[220:221], v112 offset:0x2a00
	v_mfma_f32_32x32x16_bf16 v[50:65], v[176:179], v[222:225], v[50:65]
	ds_read_b64_tr_b16 v[222:223], v112 offset:0x3200
	ds_read_b64_tr_b16 v[224:225], v112 offset:0x3a00
	s_waitcnt lgkmcnt(6)
	v_mfma_f32_32x32x16_bf16 v[34:49], v[100:103], v[180:183], v[34:49]
	ds_read_b64_tr_b16 v[180:181], v112 offset:0x400
	ds_read_b64_tr_b16 v[182:183], v112 offset:0xc00
	s_waitcnt lgkmcnt(6)
	v_mfma_f32_32x32x16_bf16 v[34:49], v[104:107], v[214:217], v[34:49]
	ds_read_b64_tr_b16 v[214:215], v112 offset:0x1400
	ds_read_b64_tr_b16 v[216:217], v112 offset:0x1c00
	s_waitcnt lgkmcnt(6)
	v_mfma_f32_32x32x16_bf16 v[34:49], v[108:111], v[218:221], v[34:49]
	ds_read_b64_tr_b16 v[218:219], v112 offset:0x2400
	ds_read_b64_tr_b16 v[220:221], v112 offset:0x2c00
	s_waitcnt lgkmcnt(6)
	v_mfma_f32_32x32x16_bf16 v[34:49], v[176:179], v[222:225], v[34:49]
	ds_read_b64_tr_b16 v[222:223], v112 offset:0x3400
	ds_read_b64_tr_b16 v[224:225], v112 offset:0x3c00
	s_waitcnt lgkmcnt(6)
	v_mfma_f32_32x32x16_bf16 v[18:33], v[100:103], v[180:183], v[18:33]
	ds_read_b64_tr_b16 v[180:181], v112 offset:0x600
	ds_read_b64_tr_b16 v[182:183], v112 offset:0xe00
	s_waitcnt lgkmcnt(6)
	v_mfma_f32_32x32x16_bf16 v[18:33], v[104:107], v[214:217], v[18:33]
	ds_read_b64_tr_b16 v[214:215], v112 offset:0x1600
	ds_read_b64_tr_b16 v[216:217], v112 offset:0x1e00
	s_waitcnt lgkmcnt(6)
	v_mfma_f32_32x32x16_bf16 v[18:33], v[108:111], v[218:221], v[18:33]
	ds_read_b64_tr_b16 v[218:219], v112 offset:0x2600
	ds_read_b64_tr_b16 v[220:221], v112 offset:0x2e00
	s_waitcnt lgkmcnt(6)
	v_mfma_f32_32x32x16_bf16 v[18:33], v[176:179], v[222:225], v[18:33]
	ds_read_b64_tr_b16 v[222:223], v112 offset:0x3600
	ds_read_b64_tr_b16 v[224:225], v112 offset:0x3e00
	s_waitcnt lgkmcnt(6)
	v_mfma_f32_32x32x16_bf16 v[2:17], v[100:103], v[180:183], v[2:17]
	v_max_f32_e32 v100, v115, v115
	v_max_f32_e32 v101, v114, v114
	v_max_f32_e32 v100, v101, v100
	v_max3_f32 v101, v116, v117, v83
	v_max3_f32 v100, v100, v82, v84
	v_max3_f32 v100, v100, v85, v118
	v_max3_f32 v101, v101, v120, v121
	s_waitcnt lgkmcnt(4)
	v_mfma_f32_32x32x16_bf16 v[2:17], v[104:107], v[214:217], v[2:17]
	v_max3_f32 v100, v100, v119, v86
	v_max3_f32 v101, v101, v88, v89
	v_max3_f32 v100, v100, v87, v122
	v_max3_f32 v101, v101, v124, v125
	v_max3_f32 v100, v100, v123, v90
	v_max3_f32 v101, v101, v92, v93
	v_max3_f32 v100, v100, v91, v126
	s_waitcnt lgkmcnt(2)
	v_mfma_f32_32x32x16_bf16 v[2:17], v[108:111], v[218:221], v[2:17]
	v_max3_f32 v101, v101, v128, v129
	v_max3_f32 v100, v100, v127, v94
	v_max3_f32 v101, v101, v96, v97
	v_max3_f32 v100, v100, v95, v101
	v_mov_b32_e32 v101, v100
	s_nop 1
	v_permlane32_swap_b32_e32 v100, v101
	s_waitcnt lgkmcnt(0)
	v_mfma_f32_32x32x16_bf16 v[2:17], v[176:179], v[222:225], v[2:17]
	v_max_f32_e32 v101, v101, v101
	v_max_f32_e32 v100, v100, v100
	v_max_f32_e32 v100, v100, v101
	v_cmp_lt_f32_e32 vcc, s40, v100
	v_mov_b32_e32 v176, 1.0
	s_cbranch_vccnz .LBB0_114
	s_branch .LBB0_111

; __device__ __forceinline__ void finishSM(f32x16& p0, f32x16& p1, float alpha, float& l_reg, bf16x8& pa0, bf16x8& pa1, bf16x8& pa2, bf16x8& pa3) {
; #pragma unroll
;   for (int r = 0; r < 16; ++r) p1[r] = __builtin_amdgcn_exp2f(p1[r]);
;   float ps = 0;
; #pragma unroll
;   for (int r = 0; r < 16; ++r) ps += p0[r];
; #pragma unroll
;   for (int r = 0; r < 16; ++r) ps += p1[r];
;   { auto rr = __builtin_amdgcn_permlane32_swap(__float_as_uint(ps), __float_as_uint(ps), false, false);
;     ps = __uint_as_float(rr[0]) + __uint_as_float(rr[1]); }
;   l_reg = l_reg * alpha + ps;
; template <bool MLA>
; __device__ __forceinline__ void qkt(f32x16& p0, f32x16& p1, const char* Ks, const char* KRs, const bf16x8* qr, const char* qrl, const f32x16& negm, int r32, int hi) {
; #pragma unroll
;   for (int d0 = 0; d0 < 8; ++d0) { int cb = (d0 * 16 + hi * 8) * 2;
;     bf16x8 b0 = *reinterpret_cast<const bf16x8*>(Ks + KSWZ(r32, cb));
;     bf16x8 b1 = *reinterpret_cast<const bf16x8*>(Ks + KSWZ(32 + r32, cb));
;     if (d0 == 0) { p0 = __builtin_amdgcn_mfma_f32_32x32x16_bf16(b0, qr[0], negm, 0, 0, 0); p1 = __builtin_amdgcn_mfma_f32_32x32x16_bf16(b1, qr[0], negm, 0, 0, 0); }
;     else { p0 = __builtin_amdgcn_mfma_f32_32x32x16_bf16(b0, qr[d0], p0, 0, 0, 0); p1 = __builtin_amdgcn_mfma_f32_32x32x16_bf16(b1, qr[d0], p1, 0, 0, 0); } }
;   if constexpr (MLA) {
; #pragma unroll
;     for (int d0 = 0; d0 < 4; ++d0) { int ch = d0 * 2 + hi;
;       bf16x8 b0 = *reinterpret_cast<const bf16x8*>(KRs + KRSWZ(r32, ch));
;       bf16x8 b1 = *reinterpret_cast<const bf16x8*>(KRs + KRSWZ(32 + r32, ch));
;       const bf16x8 qq = *reinterpret_cast<const bf16x8*>(qrl + d0 * 1024);
;       p0 = __builtin_amdgcn_mfma_f32_32x32x16_bf16(b0, qq, p0, 0, 0, 0);
;       p1 = __builtin_amdgcn_mfma_f32_32x32x16_bf16(b1, qq, p1, 0, 0, 0); }
;   }
; }
.LBB0_116:
	s_add_i32 s2, 0, 0x10000
	v_add_u32_e32 v0, s2, v210
	ds_read_b128 v[168:171], v0 offset:8192
	ds_read_b128 v[98:101], v0
	v_add_u32_e32 v0, s2, v209
	v_exp_f32_e32 v83, v83
	v_exp_f32_e32 v96, v96
	v_exp_f32_e32 v97, v97
	s_waitcnt lgkmcnt(0)
	v_mfma_f32_32x32x16_bf16 v[114:129], v[98:101], v[158:161], v[66:81]
	v_mfma_f32_32x32x16_bf16 v[98:113], v[168:171], v[158:161], v[66:81]
	ds_read_b128 v[158:161], v0 offset:8192
	ds_read_b128 v[168:171], v0
	v_add_u32_e32 v0, s2, v208
	s_waitcnt lgkmcnt(0)
	v_mfma_f32_32x32x16_bf16 v[114:129], v[168:171], v[154:157], v[114:129]
	v_mfma_f32_32x32x16_bf16 v[98:113], v[158:161], v[154:157], v[98:113]
	ds_read_b128 v[154:157], v0 offset:8192
	ds_read_b128 v[158:161], v0
	v_add_u32_e32 v0, s2, v207
	s_waitcnt lgkmcnt(0)
	v_mfma_f32_32x32x16_bf16 v[114:129], v[158:161], v[150:153], v[114:129]
	v_mfma_f32_32x32x16_bf16 v[98:113], v[154:157], v[150:153], v[98:113]
	ds_read_b128 v[150:153], v0 offset:8192
	ds_read_b128 v[154:157], v0
	v_add_u32_e32 v0, s2, v206
	s_waitcnt lgkmcnt(0)
	v_mfma_f32_32x32x16_bf16 v[114:129], v[154:157], v[146:149], v[114:129]
	v_mfma_f32_32x32x16_bf16 v[98:113], v[150:153], v[146:149], v[98:113]
	ds_read_b128 v[146:149], v0 offset:8192
	ds_read_b128 v[150:153], v0
	v_add_u32_e32 v0, s2, v205
	s_waitcnt lgkmcnt(0)
	v_mfma_f32_32x32x16_bf16 v[114:129], v[150:153], v[142:145], v[114:129]
	v_mfma_f32_32x32x16_bf16 v[98:113], v[146:149], v[142:145], v[98:113]
	ds_read_b128 v[142:145], v0 offset:8192
	ds_read_b128 v[146:149], v0
	v_add_u32_e32 v0, s2, v204
	s_waitcnt lgkmcnt(0)
	v_mfma_f32_32x32x16_bf16 v[114:129], v[146:149], v[138:141], v[114:129]
	v_mfma_f32_32x32x16_bf16 v[98:113], v[142:145], v[138:141], v[98:113]
	ds_read_b128 v[138:141], v0 offset:8192
	ds_read_b128 v[142:145], v0
	v_add_u32_e32 v0, s2, v203
	s_add_i32 s2, 0, 0x1a000
	s_waitcnt lgkmcnt(0)
	v_mfma_f32_32x32x16_bf16 v[114:129], v[142:145], v[134:137], v[114:129]
	v_exp_f32_e32 v142, v95
	v_mfma_f32_32x32x16_bf16 v[98:113], v[138:141], v[134:137], v[98:113]
	ds_read_b128 v[134:137], v0 offset:8192
	ds_read_b128 v[138:141], v0
	v_add_u32_e32 v0, s2, v200
	s_waitcnt lgkmcnt(0)
	v_mfma_f32_32x32x16_bf16 v[114:129], v[138:141], v[130:133], v[114:129]
	v_mfma_f32_32x32x16_bf16 v[98:113], v[134:137], v[130:133], v[98:113]
	ds_read_b128 v[130:133], v0
	ds_read_b128 v[134:137], v0 offset:4096
	ds_read_b128 v[138:141], v198
	v_add_u32_e32 v0, s2, v201
	s_waitcnt lgkmcnt(0)
	v_mfma_f32_32x32x16_bf16 v[114:129], v[130:133], v[138:141], v[114:129]
	v_mfma_f32_32x32x16_bf16 v[98:113], v[134:137], v[138:141], v[98:113]
	ds_read_b128 v[130:133], v0
	ds_read_b128 v[134:137], v0 offset:4096
	ds_read_b128 v[138:141], v198 offset:1024
	v_add_u32_e32 v0, s2, v199
	s_waitcnt lgkmcnt(0)
	v_mfma_f32_32x32x16_bf16 v[114:129], v[130:133], v[138:141], v[114:129]
	v_mfma_f32_32x32x16_bf16 v[98:113], v[134:137], v[138:141], v[98:113]
	ds_read_b128 v[130:133], v0
	ds_read_b128 v[134:137], v0 offset:4096
	ds_read_b128 v[138:141], v198 offset:2048
	v_add_u32_e32 v0, s2, v202
	s_waitcnt lgkmcnt(0)
	v_mfma_f32_32x32x16_bf16 v[114:129], v[130:133], v[138:141], v[114:129]
	v_mfma_f32_32x32x16_bf16 v[98:113], v[134:137], v[138:141], v[98:113]
	ds_read_b128 v[130:133], v0
	ds_read_b128 v[134:137], v0 offset:4096
	ds_read_b128 v[138:141], v198 offset:3072
	v_add_f32_e32 v0, 0, v227
	v_add_f32_e32 v0, v229, v0
	v_add_f32_e32 v0, v225, v0
	v_add_f32_e32 v0, v228, v0
	v_add_f32_e32 v0, v224, v0
	v_add_f32_e32 v0, v226, v0
	v_add_f32_e32 v0, v222, v0
	v_add_f32_e32 v0, v223, v0
	v_add_f32_e32 v0, v219, v0
	v_add_f32_e32 v0, v221, v0
	v_add_f32_e32 v0, v218, v0
	v_add_f32_e32 v0, v220, v0
	s_waitcnt lgkmcnt(0)
; __device__ __forceinline__ void finishSM(f32x16& p0, f32x16& p1, float alpha, float& l_reg, bf16x8& pa0, bf16x8& pa1, bf16x8& pa2, bf16x8& pa3) {
; #pragma unroll
;   for (int r = 0; r < 16; ++r) p1[r] = __builtin_amdgcn_exp2f(p1[r]);
;   float ps = 0;
; #pragma unroll
;   for (int r = 0; r < 16; ++r) ps += p0[r];
; #pragma unroll
;   for (int r = 0; r < 16; ++r) ps += p1[r];
;   { auto rr = __builtin_amdgcn_permlane32_swap(__float_as_uint(ps), __float_as_uint(ps), false, false);
;     ps = __uint_as_float(rr[0]) + __uint_as_float(rr[1]); }
;   l_reg = l_reg * alpha + ps;
;     ...
;   PK4(p0, 0, pa0); PK4(p0, 8, pa1); PK4(p1, 0, pa2); PK4(p1, 8, pa3);
;     ...
; }
; template <bool MLA>
; __device__ __forceinline__ void qkt(f32x16& p0, f32x16& p1, const char* Ks, const char* KRs, const bf16x8* qr, const char* qrl, const f32x16& negm, int r32, int hi) {
; #pragma unroll
;   for (int d0 = 0; d0 < 8; ++d0) { int cb = (d0 * 16 + hi * 8) * 2;
;     bf16x8 b0 = *reinterpret_cast<const bf16x8*>(Ks + KSWZ(r32, cb));
;     bf16x8 b1 = *reinterpret_cast<const bf16x8*>(Ks + KSWZ(32 + r32, cb));
;     if (d0 == 0) { p0 = __builtin_amdgcn_mfma_f32_32x32x16_bf16(b0, qr[0], negm, 0, 0, 0); p1 = __builtin_amdgcn_mfma_f32_32x32x16_bf16(b1, qr[0], negm, 0, 0, 0); }
;     else { p0 = __builtin_amdgcn_mfma_f32_32x32x16_bf16(b0, qr[d0], p0, 0, 0, 0); p1 = __builtin_amdgcn_mfma_f32_32x32x16_bf16(b1, qr[d0], p1, 0, 0, 0); } }
;   if constexpr (MLA) {
; #pragma unroll
;     for (int d0 = 0; d0 < 4; ++d0) { int ch = d0 * 2 + hi;
;       bf16x8 b0 = *reinterpret_cast<const bf16x8*>(KRs + KRSWZ(r32, ch));
;       bf16x8 b1 = *reinterpret_cast<const bf16x8*>(KRs + KRSWZ(32 + r32, ch));
;       const bf16x8 qq = *reinterpret_cast<const bf16x8*>(qrl + d0 * 1024);
;       p0 = __builtin_amdgcn_mfma_f32_32x32x16_bf16(b0, qq, p0, 0, 0, 0);
;       p1 = __builtin_amdgcn_mfma_f32_32x32x16_bf16(b1, qq, p1, 0, 0, 0); }
;   }
; }
; __device__ __forceinline__ int v_st(int k, int c) { const int kk = (k & ~0xC) | ((k & 4) << 1) | ((k & 8) >> 1); return ((kk >> 3) * 4 + (c >> 5)) * 512 + ((kk & 7) * 32 + (c & 31)) * 2; }
; __device__ __forceinline__ int v_rd_base(int lane) { return ((lane & 3) << 3) | (((lane >> 2) & 3) << 6) | (((lane >> 4) & 1) << 5) | (((lane >> 5) & 1) << 8); }
; template <int OFF> __device__ __forceinline__ s16x4 tr_read(int vb) {
	v_mfma_f32_32x32x16_bf16 v[114:129], v[130:133], v[138:141], v[114:129]
	v_exp_f32_e32 v130, v82
	v_add_f32_e32 v0, v215, v0
	v_add_f32_e32 v0, v217, v0
	v_exp_f32_e32 v131, v84
	v_add_f32_e32 v0, v214, v0
	v_exp_f32_e32 v132, v85
	v_add_f32_e32 v0, v216, v0
	v_exp_f32_e32 v133, v86
	v_add_f32_e32 v0, v130, v0
	v_mfma_f32_32x32x16_bf16 v[98:113], v[134:137], v[138:141], v[98:113]
	v_exp_f32_e32 v134, v87
	v_add_f32_e32 v0, v83, v0
	v_exp_f32_e32 v135, v88
	v_add_f32_e32 v0, v131, v0
	v_exp_f32_e32 v136, v89
	v_add_f32_e32 v0, v132, v0
	v_exp_f32_e32 v137, v90
	v_add_f32_e32 v0, v133, v0
	v_exp_f32_e32 v138, v91
	v_add_f32_e32 v0, v134, v0
	v_exp_f32_e32 v139, v92
	v_add_f32_e32 v0, v135, v0
	v_exp_f32_e32 v140, v93
	v_add_f32_e32 v0, v136, v0
	v_exp_f32_e32 v141, v94
	v_add_f32_e32 v0, v137, v0
	v_add_f32_e32 v0, v138, v0
	v_add_f32_e32 v0, v139, v0
	v_add_f32_e32 v0, v140, v0
	v_add_f32_e32 v0, v141, v0
	v_add_f32_e32 v0, v142, v0
	v_add_f32_e32 v0, v96, v0
	v_add_f32_e32 v0, v97, v0
	v_mov_b32_e32 v82, v0
	v_cvt_pk_bf16_f32 v84, v227, v229
	v_cvt_pk_bf16_f32 v85, v225, v228
	v_cvt_pk_bf16_f32 v86, v224, v226
	s_nop 1
	v_permlane32_swap_b32_e32 v0, v82
	v_cvt_pk_bf16_f32 v87, v222, v223
	v_permlane32_swap_b32_e32 v84, v86
	v_cvt_pk_bf16_f32 v88, v219, v221
	v_cvt_pk_bf16_f32 v89, v218, v220
	v_cvt_pk_bf16_f32 v90, v215, v217
	v_cvt_pk_bf16_f32 v91, v214, v216
	v_cvt_pk_bf16_f32 v92, v130, v83
	v_cvt_pk_bf16_f32 v93, v131, v132
	v_cvt_pk_bf16_f32 v94, v133, v134
	v_cvt_pk_bf16_f32 v95, v135, v136
	v_cvt_pk_bf16_f32 v130, v137, v138
	v_cvt_pk_bf16_f32 v131, v139, v140
	v_cvt_pk_bf16_f32 v132, v141, v142
	v_cvt_pk_bf16_f32 v133, v96, v97
	v_permlane32_swap_b32_e32 v85, v87
	v_permlane32_swap_b32_e32 v88, v90
	v_permlane32_swap_b32_e32 v89, v91
	v_permlane32_swap_b32_e32 v92, v94
	v_permlane32_swap_b32_e32 v93, v95
	v_permlane32_swap_b32_e32 v130, v132
	v_permlane32_swap_b32_e32 v131, v133
	ds_read_b64_tr_b16 v[134:135], v197 offset:0
	ds_read_b64_tr_b16 v[136:137], v197 offset:0x800
	ds_read_b64_tr_b16 v[138:139], v197 offset:0x1000
	ds_read_b64_tr_b16 v[140:141], v197 offset:0x1800
	ds_read_b64_tr_b16 v[142:143], v197 offset:0x2000
	ds_read_b64_tr_b16 v[144:145], v197 offset:0x2800
	ds_read_b64_tr_b16 v[146:147], v197 offset:0x3000
	ds_read_b64_tr_b16 v[148:149], v197 offset:0x3800
	s_waitcnt lgkmcnt(0)
	s_nop 0
	v_mfma_f32_32x32x16_bf16 v[50:65], v[84:87], v[134:137], v[50:65]
	ds_read_b64_tr_b16 v[134:135], v197 offset:0x200
	ds_read_b64_tr_b16 v[136:137], v197 offset:0xa00
	v_mfma_f32_32x32x16_bf16 v[50:65], v[88:91], v[138:141], v[50:65]
	ds_read_b64_tr_b16 v[138:139], v197 offset:0x1200
	ds_read_b64_tr_b16 v[140:141], v197 offset:0x1a00
	v_mfma_f32_32x32x16_bf16 v[50:65], v[92:95], v[142:145], v[50:65]
	ds_read_b64_tr_b16 v[142:143], v197 offset:0x2200
	ds_read_b64_tr_b16 v[144:145], v197 offset:0x2a00
	v_mfma_f32_32x32x16_bf16 v[50:65], v[130:133], v[146:149], v[50:65]
	ds_read_b64_tr_b16 v[146:147], v197 offset:0x3200
	ds_read_b64_tr_b16 v[148:149], v197 offset:0x3a00
	s_waitcnt lgkmcnt(0)
	v_mfma_f32_32x32x16_bf16 v[34:49], v[84:87], v[134:137], v[34:49]
	ds_read_b64_tr_b16 v[134:135], v197 offset:0x400
	ds_read_b64_tr_b16 v[136:137], v197 offset:0xc00
	v_mfma_f32_32x32x16_bf16 v[34:49], v[88:91], v[138:141], v[34:49]
	ds_read_b64_tr_b16 v[138:139], v197 offset:0x1400
	ds_read_b64_tr_b16 v[140:141], v197 offset:0x1c00
	v_mfma_f32_32x32x16_bf16 v[34:49], v[92:95], v[142:145], v[34:49]
	ds_read_b64_tr_b16 v[142:143], v197 offset:0x2400
	ds_read_b64_tr_b16 v[144:145], v197 offset:0x2c00
	v_mfma_f32_32x32x16_bf16 v[34:49], v[130:133], v[146:149], v[34:49]
	ds_read_b64_tr_b16 v[146:147], v197 offset:0x3400
	ds_read_b64_tr_b16 v[148:149], v197 offset:0x3c00
	s_waitcnt lgkmcnt(0)
	v_mfma_f32_32x32x16_bf16 v[18:33], v[84:87], v[134:137], v[18:33]
	ds_read_b64_tr_b16 v[134:135], v197 offset:0x600
	ds_read_b64_tr_b16 v[136:137], v197 offset:0xe00
	v_mfma_f32_32x32x16_bf16 v[18:33], v[88:91], v[138:141], v[18:33]
	ds_read_b64_tr_b16 v[138:139], v197 offset:0x1600
	ds_read_b64_tr_b16 v[140:141], v197 offset:0x1e00
	v_mfma_f32_32x32x16_bf16 v[18:33], v[92:95], v[142:145], v[18:33]
	ds_read_b64_tr_b16 v[142:143], v197 offset:0x2600
	ds_read_b64_tr_b16 v[144:145], v197 offset:0x2e00
	v_mfma_f32_32x32x16_bf16 v[18:33], v[130:133], v[146:149], v[18:33]
	ds_read_b64_tr_b16 v[146:147], v197 offset:0x3600
	ds_read_b64_tr_b16 v[148:149], v197 offset:0x3e00
	s_waitcnt lgkmcnt(0)
	v_mfma_f32_32x32x16_bf16 v[2:17], v[84:87], v[134:137], v[2:17]
	v_max_f32_e32 v83, v115, v115
	v_max_f32_e32 v84, v114, v114
	v_max_f32_e32 v83, v84, v83
	v_max3_f32 v84, v116, v117, v99
	v_max3_f32 v83, v83, v98, v100
	v_max3_f32 v83, v83, v101, v118
	v_max3_f32 v84, v84, v120, v121
	v_mfma_f32_32x32x16_bf16 v[2:17], v[88:91], v[138:141], v[2:17]
	v_max3_f32 v83, v83, v119, v102
	v_max3_f32 v84, v84, v104, v105
	v_max3_f32 v83, v83, v103, v122
	v_max3_f32 v84, v84, v124, v125
	v_max3_f32 v83, v83, v123, v106
	v_max3_f32 v84, v84, v108, v109
	v_max3_f32 v83, v83, v107, v126
	v_mfma_f32_32x32x16_bf16 v[2:17], v[92:95], v[142:145], v[2:17]
	v_max3_f32 v84, v84, v128, v129
	v_max3_f32 v83, v83, v127, v110
	v_max3_f32 v84, v84, v112, v113
	v_max3_f32 v83, v83, v111, v84
	v_mov_b32_e32 v84, v83
	s_nop 1
	v_permlane32_swap_b32_e32 v83, v84
	v_mfma_f32_32x32x16_bf16 v[2:17], v[130:133], v[146:149], v[2:17]
	v_max_f32_e32 v84, v84, v84
	v_max_f32_e32 v83, v83, v83
	v_max_f32_e32 v84, v83, v84
	v_cmp_lt_f32_e32 vcc, s40, v84
	v_mov_b32_e32 v83, 1.0
	s_cbranch_vccnz .LBB0_146
	s_branch .LBB0_121

; __device__ __forceinline__ void finishSM(f32x16& p0, f32x16& p1, float alpha, float& l_reg, bf16x8& pa0, bf16x8& pa1, bf16x8& pa2, bf16x8& pa3) {
; #pragma unroll
;   for (int r = 0; r < 16; ++r) p1[r] = __builtin_amdgcn_exp2f(p1[r]);
;   float ps = 0;
; #pragma unroll
;   for (int r = 0; r < 16; ++r) ps += p0[r];
; #pragma unroll
;   for (int r = 0; r < 16; ++r) ps += p1[r];
;   { auto rr = __builtin_amdgcn_permlane32_swap(__float_as_uint(ps), __float_as_uint(ps), false, false);
;     ps = __uint_as_float(rr[0]) + __uint_as_float(rr[1]); }
;   l_reg = l_reg * alpha + ps;
; template <bool MLA>
; __device__ __forceinline__ void qkt(f32x16& p0, f32x16& p1, const char* Ks, const char* KRs, const bf16x8* qr, const char* qrl, const f32x16& negm, int r32, int hi) {
; #pragma unroll
;   for (int d0 = 0; d0 < 8; ++d0) { int cb = (d0 * 16 + hi * 8) * 2;
;     bf16x8 b0 = *reinterpret_cast<const bf16x8*>(Ks + KSWZ(r32, cb));
;     bf16x8 b1 = *reinterpret_cast<const bf16x8*>(Ks + KSWZ(32 + r32, cb));
;     if (d0 == 0) { p0 = __builtin_amdgcn_mfma_f32_32x32x16_bf16(b0, qr[0], negm, 0, 0, 0); p1 = __builtin_amdgcn_mfma_f32_32x32x16_bf16(b1, qr[0], negm, 0, 0, 0); }
;     else { p0 = __builtin_amdgcn_mfma_f32_32x32x16_bf16(b0, qr[d0], p0, 0, 0, 0); p1 = __builtin_amdgcn_mfma_f32_32x32x16_bf16(b1, qr[d0], p1, 0, 0, 0); } }
.LBB0_125:
	s_mov_b32 s13, s16
	s_mov_b32 s16, s23
	s_lshl_b32 s8, s17, 14
	s_add_i32 s23, s8, 0
	s_add_i32 s32, s23, s14
	s_lshl_b32 s19, s13, 14
	s_add_i32 s8, s19, 0
	v_add_u32_e32 v98, s8, v199
	ds_read_b128 v[220:223], v98 offset:57344
	ds_read_b128 v[98:101], v98 offset:49152
	v_add_u32_e32 v201, s8, v198
	s_add_u32 vcc_lo, s2, s62
	s_addc_u32 vcc_hi, s3, s63
	s_add_i32 m0, s32, 0xc000
	v_lshl_add_u64 v[250:251], v[168:169], 0, vcc
	global_load_lds_dwordx4 v[250:251], off
	v_exp_f32_e32 v203, v82
	v_add_f32_e32 v82, 0, v217
	v_add_f32_e32 v82, v219, v82
	s_waitcnt lgkmcnt(0)
	v_mfma_f32_32x32x16_bf16 v[114:129], v[98:101], v[158:161], v[66:81]
	v_add_f32_e32 v82, v215, v82
	v_add_f32_e32 v82, v218, v82
	v_add_f32_e32 v82, v214, v82
	v_add_f32_e32 v82, v216, v82
	v_add_f32_e32 v82, v212, v82
	v_add_f32_e32 v82, v213, v82
	v_add_f32_e32 v82, v209, v82
	v_mfma_f32_32x32x16_bf16 v[98:113], v[220:223], v[158:161], v[66:81]
	ds_read_b128 v[220:223], v201 offset:57344
	ds_read_b128 v[224:227], v201 offset:49152
	v_add_u32_e32 v201, s8, v197
	s_add_u32 vcc_lo, s2, 0x1c3c1600
	s_addc_u32 vcc_hi, s3, 0
	s_mov_b32 m0, s32
	v_lshl_add_u64 v[250:251], v[0:1], 0, vcc
	global_load_lds_dwordx4 v[250:251], off
	v_add_f32_e32 v82, v211, v82
	v_add_f32_e32 v82, v208, v82
	v_add_f32_e32 v82, v210, v82
	v_add_f32_e32 v82, v205, v82
	v_add_f32_e32 v82, v207, v82
	s_waitcnt lgkmcnt(0)
	v_mfma_f32_32x32x16_bf16 v[98:113], v[220:223], v[154:157], v[98:113]
	v_add_f32_e32 v82, v204, v82
	v_add_f32_e32 v82, v206, v82
	v_add_f32_e32 v82, v203, v82
	v_exp_f32_e32 v228, v91
	v_exp_f32_e32 v229, v92
	v_exp_f32_e32 v234, v93
	v_exp_f32_e32 v235, v94
	v_mfma_f32_32x32x16_bf16 v[114:129], v[224:227], v[154:157], v[114:129]
	ds_read_b128 v[220:223], v201 offset:57344
	ds_read_b128 v[224:227], v201 offset:49152
	v_add_u32_e32 v201, s8, v196
	s_add_u32 vcc_lo, s2, s62
	s_addc_u32 vcc_hi, s3, s63
	s_add_i32 m0, s32, 0xc400
	v_lshl_add_u64 v[250:251], v[170:171], 0, vcc
	global_load_lds_dwordx4 v[250:251], off
	v_exp_f32_e32 v236, v95
	v_exp_f32_e32 v237, v96
	v_exp_f32_e32 v97, v97
	s_lshl_b32 s24, s16, 14
	s_waitcnt lgkmcnt(0)
	v_mfma_f32_32x32x16_bf16 v[98:113], v[220:223], v[150:153], v[98:113]
	v_mfma_f32_32x32x16_bf16 v[114:129], v[224:227], v[150:153], v[114:129]
	ds_read_b128 v[220:223], v201 offset:57344
	ds_read_b128 v[224:227], v201 offset:49152
	v_add_u32_e32 v201, s8, v195
	s_add_u32 vcc_lo, s2, 0x1c3c1680
	s_addc_u32 vcc_hi, s3, 0
	s_add_i32 m0, s32, 0x400
	v_lshl_add_u64 v[250:251], v[0:1], 0, vcc
	global_load_lds_dwordx4 v[250:251], off
	s_waitcnt lgkmcnt(0)
	v_mfma_f32_32x32x16_bf16 v[98:113], v[220:223], v[146:149], v[98:113]
	v_mfma_f32_32x32x16_bf16 v[114:129], v[224:227], v[146:149], v[114:129]
	ds_read_b128 v[220:223], v201 offset:57344
	ds_read_b128 v[224:227], v201 offset:49152
	v_add_u32_e32 v201, s8, v183
	s_waitcnt lgkmcnt(0)
	v_mfma_f32_32x32x16_bf16 v[98:113], v[220:223], v[142:145], v[98:113]
	v_mfma_f32_32x32x16_bf16 v[114:129], v[224:227], v[142:145], v[114:129]
	ds_read_b128 v[220:223], v201 offset:57344
	ds_read_b128 v[224:227], v201 offset:49152
	v_add_u32_e32 v201, s8, v193
	s_waitcnt lgkmcnt(0)
	v_mfma_f32_32x32x16_bf16 v[98:113], v[220:223], v[138:141], v[98:113]
	v_mfma_f32_32x32x16_bf16 v[114:129], v[224:227], v[138:141], v[114:129]
	ds_read_b128 v[220:223], v201 offset:57344
	ds_read_b128 v[224:227], v201 offset:49152
	v_add_u32_e32 v201, s8, v194
	s_waitcnt lgkmcnt(0)
	v_mfma_f32_32x32x16_bf16 v[98:113], v[220:223], v[134:137], v[98:113]
	v_mfma_f32_32x32x16_bf16 v[114:129], v[224:227], v[134:137], v[114:129]
	ds_read_b128 v[220:223], v201 offset:57344
	ds_read_b128 v[224:227], v201 offset:49152
	s_waitcnt lgkmcnt(0)
	v_mfma_f32_32x32x16_bf16 v[98:113], v[220:223], v[130:133], v[98:113]
	v_exp_f32_e32 v220, v83
	v_exp_f32_e32 v221, v84
	v_exp_f32_e32 v222, v85
	v_exp_f32_e32 v223, v86
	v_add_f32_e32 v82, v220, v82
	v_add_f32_e32 v82, v221, v82
	v_add_f32_e32 v82, v222, v82
	v_mfma_f32_32x32x16_bf16 v[114:129], v[224:227], v[130:133], v[114:129]
	v_exp_f32_e32 v224, v87
	v_exp_f32_e32 v225, v88
	v_exp_f32_e32 v226, v89
	v_exp_f32_e32 v227, v90
	v_add_f32_e32 v82, v223, v82
	v_add_f32_e32 v82, v224, v82
	v_add_f32_e32 v82, v225, v82
	v_add_f32_e32 v82, v226, v82
	v_add_f32_e32 v82, v227, v82
	v_add_f32_e32 v82, v228, v82
	v_add_f32_e32 v82, v229, v82
	v_add_f32_e32 v82, v234, v82
	v_add_f32_e32 v82, v235, v82
	v_add_f32_e32 v82, v236, v82
	v_add_f32_e32 v82, v237, v82
	v_add_f32_e32 v201, v97, v82
	v_cvt_pk_bf16_f32 v82, v217, v219
	v_cvt_pk_bf16_f32 v83, v215, v218
	v_cvt_pk_bf16_f32 v84, v214, v216
	v_cvt_pk_bf16_f32 v85, v212, v213
	v_cvt_pk_bf16_f32 v86, v209, v211
	v_cvt_pk_bf16_f32 v87, v208, v210
	v_cvt_pk_bf16_f32 v88, v205, v207
	v_cvt_pk_bf16_f32 v89, v204, v206
	v_cvt_pk_bf16_f32 v90, v203, v220
	v_cvt_pk_bf16_f32 v91, v221, v222
	v_cvt_pk_bf16_f32 v92, v223, v224
	v_cvt_pk_bf16_f32 v93, v225, v226
	v_cvt_pk_bf16_f32 v94, v227, v228
	v_cvt_pk_bf16_f32 v95, v229, v234
	v_cvt_pk_bf16_f32 v96, v235, v236
	v_cvt_pk_bf16_f32 v97, v237, v97
	v_add_u32_e32 v203, s24, v182
	ds_read_b64_tr_b16 v[204:205], v203 offset:0
	ds_read_b64_tr_b16 v[206:207], v203 offset:0x800
	ds_read_b64_tr_b16 v[208:209], v203 offset:0x1000
	ds_read_b64_tr_b16 v[210:211], v203 offset:0x1800
	ds_read_b64_tr_b16 v[212:213], v203 offset:0x2000
	ds_read_b64_tr_b16 v[214:215], v203 offset:0x2800
	ds_read_b64_tr_b16 v[216:217], v203 offset:0x3000
	ds_read_b64_tr_b16 v[218:219], v203 offset:0x3800
	s_waitcnt lgkmcnt(0)
; #define SBAR() __builtin_amdgcn_sched_barrier(0)
; __device__ __forceinline__ float max3f(float a, float b, float c) { return __builtin_fmaxf(__builtin_fmaxf(a, b), c); }
; template <bool FIRST, bool MLA>
; __device__ __forceinline__ void partialSM(f32x16& p0, f32x16& p1, f32x16& negm, float& m_reg, float& alpha) {
;   float a = max3f(p0[0], p0[1], p1[0]), b = max3f(p0[2], p0[3], p1[1]); a = max3f(a, p1[2], p1[3]);
; #pragma unroll
;   for (int r = 4; r < 16; r += 4) { a = max3f(a, p0[r], p0[r + 1]); b = max3f(b, p0[r + 2], p0[r + 3]); a = max3f(a, p1[r], p1[r + 1]); b = max3f(b, p1[r + 2], p1[r + 3]); }
;   float pmax = fmaxf(a, b);
;   { auto rr = __builtin_amdgcn_permlane32_swap(__float_as_uint(pmax), __float_as_uint(pmax), false, false);
;     pmax = fmaxf(__uint_as_float(rr[0]), __uint_as_float(rr[1])); }
;   alpha = 1.f;
;   if constexpr (MLA) {
;     if (FIRST) m_reg = pmax;
;     else if (!__builtin_expect(__all(pmax - m_reg <= THR2), 1)) { const float mn = fmaxf(m_reg, pmax); alpha = __builtin_amdgcn_exp2f(m_reg - mn); m_reg = mn; }
; #pragma unroll
;     for (int r = 0; r < 16; ++r) { p0[r] -= m_reg; p1[r] -= m_reg; }
;   } else
;   if (FIRST || __builtin_expect(__any(pmax > THR2), 0)) {
; template <int D0> __device__ __forceinline__ void pv_one(f32x16& od, int vb, bf16x8 pa0, bf16x8 pa1, bf16x8 pa2, bf16x8 pa3) {
;   const s16x4 l0 = tr_read<v_rd_off(D0, 0, 0)>(vb), h0 = tr_read<v_rd_off(D0, 0, 1)>(vb), l1 = tr_read<v_rd_off(D0, 1, 0)>(vb), h1 = tr_read<v_rd_off(D0, 1, 1)>(vb);
;   const s16x4 l2 = tr_read<v_rd_off(D0, 2, 0)>(vb), h2 = tr_read<v_rd_off(D0, 2, 1)>(vb), l3 = tr_read<v_rd_off(D0, 3, 0)>(vb), h3 = tr_read<v_rd_off(D0, 3, 1)>(vb);
;   asm volatile("s_waitcnt lgkmcnt(0)" ::: "memory"); SBAR();
;     ...
;   od = __builtin_amdgcn_mfma_f32_32x32x16_bf16(pa0, PK(l0, h0), od, 0, 0, 0);
;   od = __builtin_amdgcn_mfma_f32_32x32x16_bf16(pa1, PK(l1, h1), od, 0, 0, 0);
;   od = __builtin_amdgcn_mfma_f32_32x32x16_bf16(pa2, PK(l2, h2), od, 0, 0, 0);
;   od = __builtin_amdgcn_mfma_f32_32x32x16_bf16(pa3, PK(l3, h3), od, 0, 0, 0);
;     ...
; }
; __device__ __forceinline__ void pv_d0(f32x16* o, int vb, bf16x8 pa0, bf16x8 pa1, bf16x8 pa2, bf16x8 pa3) {
;   pv_one<0>(o[0], vb, pa0, pa1, pa2, pa3); pv_one<1>(o[1], vb, pa0, pa1, pa2, pa3); pv_one<2>(o[2], vb, pa0, pa1, pa2, pa3); pv_one<3>(o[3], vb, pa0, pa1, pa2, pa3);
	v_mov_b32_e32 v202, v201
	s_nop 1
	v_permlane32_swap_b32_e32 v201, v202
	v_permlane32_swap_b32_e32 v82, v84
	v_permlane32_swap_b32_e32 v83, v85
	v_permlane32_swap_b32_e32 v86, v88
	v_permlane32_swap_b32_e32 v87, v89
	v_permlane32_swap_b32_e32 v90, v92
	v_permlane32_swap_b32_e32 v91, v93
	v_permlane32_swap_b32_e32 v94, v96
	v_permlane32_swap_b32_e32 v95, v97
	v_mfma_f32_32x32x16_bf16 v[2:17], v[82:85], v[204:207], v[2:17]
	ds_read_b64_tr_b16 v[204:205], v203 offset:0x200
	ds_read_b64_tr_b16 v[206:207], v203 offset:0xa00
	v_mfma_f32_32x32x16_bf16 v[2:17], v[86:89], v[208:211], v[2:17]
	ds_read_b64_tr_b16 v[208:209], v203 offset:0x1200
	ds_read_b64_tr_b16 v[210:211], v203 offset:0x1a00
	v_mfma_f32_32x32x16_bf16 v[2:17], v[90:93], v[212:215], v[2:17]
	ds_read_b64_tr_b16 v[212:213], v203 offset:0x2200
	ds_read_b64_tr_b16 v[214:215], v203 offset:0x2a00
	v_mfma_f32_32x32x16_bf16 v[2:17], v[94:97], v[216:219], v[2:17]
	ds_read_b64_tr_b16 v[216:217], v203 offset:0x3200
	ds_read_b64_tr_b16 v[218:219], v203 offset:0x3a00
	s_waitcnt lgkmcnt(6)
	v_mfma_f32_32x32x16_bf16 v[50:65], v[82:85], v[204:207], v[50:65]
	ds_read_b64_tr_b16 v[204:205], v203 offset:0x400
	ds_read_b64_tr_b16 v[206:207], v203 offset:0xc00
	s_waitcnt lgkmcnt(6)
	v_mfma_f32_32x32x16_bf16 v[50:65], v[86:89], v[208:211], v[50:65]
	ds_read_b64_tr_b16 v[208:209], v203 offset:0x1400
	ds_read_b64_tr_b16 v[210:211], v203 offset:0x1c00
	s_waitcnt lgkmcnt(6)
	v_mfma_f32_32x32x16_bf16 v[50:65], v[90:93], v[212:215], v[50:65]
	ds_read_b64_tr_b16 v[212:213], v203 offset:0x2400
	ds_read_b64_tr_b16 v[214:215], v203 offset:0x2c00
	s_waitcnt lgkmcnt(6)
	v_mfma_f32_32x32x16_bf16 v[50:65], v[94:97], v[216:219], v[50:65]
	ds_read_b64_tr_b16 v[216:217], v203 offset:0x3400
	ds_read_b64_tr_b16 v[218:219], v203 offset:0x3c00
	s_waitcnt lgkmcnt(6)
	v_mfma_f32_32x32x16_bf16 v[34:49], v[82:85], v[204:207], v[34:49]
	ds_read_b64_tr_b16 v[204:205], v203 offset:0x600
	ds_read_b64_tr_b16 v[206:207], v203 offset:0xe00
	s_waitcnt lgkmcnt(6)
	v_mfma_f32_32x32x16_bf16 v[34:49], v[86:89], v[208:211], v[34:49]
	ds_read_b64_tr_b16 v[208:209], v203 offset:0x1600
	ds_read_b64_tr_b16 v[210:211], v203 offset:0x1e00
	s_waitcnt lgkmcnt(6)
	v_mfma_f32_32x32x16_bf16 v[34:49], v[90:93], v[212:215], v[34:49]
	ds_read_b64_tr_b16 v[212:213], v203 offset:0x2600
	ds_read_b64_tr_b16 v[214:215], v203 offset:0x2e00
	s_waitcnt lgkmcnt(6)
	v_mfma_f32_32x32x16_bf16 v[34:49], v[94:97], v[216:219], v[34:49]
	ds_read_b64_tr_b16 v[216:217], v203 offset:0x3600
	ds_read_b64_tr_b16 v[218:219], v203 offset:0x3e00
	s_waitcnt lgkmcnt(6)
	v_mfma_f32_32x32x16_bf16 v[18:33], v[82:85], v[204:207], v[18:33]
	v_max_f32_e32 v82, v115, v115
	v_max_f32_e32 v83, v114, v114
	v_max_f32_e32 v82, v83, v82
	v_max3_f32 v83, v116, v117, v99
	v_max3_f32 v82, v82, v98, v100
	v_max3_f32 v82, v82, v101, v118
	v_max3_f32 v83, v83, v120, v121
	s_waitcnt lgkmcnt(4)
	v_mfma_f32_32x32x16_bf16 v[18:33], v[86:89], v[208:211], v[18:33]
	v_max3_f32 v82, v82, v119, v102
	v_max3_f32 v83, v83, v104, v105
	v_max3_f32 v82, v82, v103, v122
	v_max3_f32 v83, v83, v124, v125
	v_max3_f32 v82, v82, v123, v106
	v_max3_f32 v83, v83, v108, v109
	v_max3_f32 v82, v82, v107, v126
	s_waitcnt lgkmcnt(2)
	v_mfma_f32_32x32x16_bf16 v[18:33], v[90:93], v[212:215], v[18:33]
	v_max3_f32 v83, v83, v128, v129
	v_max3_f32 v82, v82, v127, v110
	v_max3_f32 v83, v83, v112, v113
	v_max3_f32 v82, v82, v111, v83
	v_mov_b32_e32 v83, v82
	s_nop 1
	v_permlane32_swap_b32_e32 v82, v83
	s_waitcnt lgkmcnt(0)
	v_mfma_f32_32x32x16_bf16 v[18:33], v[94:97], v[216:219], v[18:33]
	v_max_f32_e32 v83, v83, v83
	v_max_f32_e32 v82, v82, v82
	v_max_f32_e32 v82, v82, v83
	v_cmp_lt_f32_e32 vcc, s40, v82
	s_cbranch_vccnz .LBB0_137
	v_mov_b32_e32 v203, 1.0
	s_branch .LBB0_130

; template <bool FIRST, bool MLA>
; __device__ __forceinline__ void partialSM(f32x16& p0, f32x16& p1, f32x16& negm, float& m_reg, float& alpha) {
;     ...
;   for (int r = 0; r < 16; ++r) p0[r] = __builtin_amdgcn_exp2f(p0[r]);
; }
; __device__ __forceinline__ void finishSM(f32x16& p0, f32x16& p1, float alpha, float& l_reg, bf16x8& pa0, bf16x8& pa1, bf16x8& pa2, bf16x8& pa3) {
; #pragma unroll
;   for (int r = 0; r < 16; ++r) p1[r] = __builtin_amdgcn_exp2f(p1[r]);
;   float ps = 0;
; #pragma unroll
;   for (int r = 0; r < 16; ++r) ps += p0[r];
; #pragma unroll
;   for (int r = 0; r < 16; ++r) ps += p1[r];
;   { auto rr = __builtin_amdgcn_permlane32_swap(__float_as_uint(ps), __float_as_uint(ps), false, false);
;     ps = __uint_as_float(rr[0]) + __uint_as_float(rr[1]); }
;   l_reg = l_reg * alpha + ps;
;     ...
;   PK4(p0, 0, pa0); PK4(p0, 8, pa1); PK4(p1, 0, pa2); PK4(p1, 8, pa3);
; template <bool MLA>
; __device__ __forceinline__ void qkt(f32x16& p0, f32x16& p1, const char* Ks, const char* KRs, const bf16x8* qr, const char* qrl, const f32x16& negm, int r32, int hi) {
; #pragma unroll
;   for (int d0 = 0; d0 < 8; ++d0) { int cb = (d0 * 16 + hi * 8) * 2;
;     bf16x8 b0 = *reinterpret_cast<const bf16x8*>(Ks + KSWZ(r32, cb));
;     bf16x8 b1 = *reinterpret_cast<const bf16x8*>(Ks + KSWZ(32 + r32, cb));
;     if (d0 == 0) { p0 = __builtin_amdgcn_mfma_f32_32x32x16_bf16(b0, qr[0], negm, 0, 0, 0); p1 = __builtin_amdgcn_mfma_f32_32x32x16_bf16(b1, qr[0], negm, 0, 0, 0); }
;     else { p0 = __builtin_amdgcn_mfma_f32_32x32x16_bf16(b0, qr[d0], p0, 0, 0, 0); p1 = __builtin_amdgcn_mfma_f32_32x32x16_bf16(b1, qr[d0], p1, 0, 0, 0); } }
.LBB0_130:
	s_waitcnt vmcnt(0)
	v_exp_f32_e32 v208, v114
	v_exp_f32_e32 v209, v115
	v_exp_f32_e32 v210, v116
	v_exp_f32_e32 v211, v117
	v_exp_f32_e32 v212, v118
	v_exp_f32_e32 v213, v119
	v_exp_f32_e32 v214, v120
	v_exp_f32_e32 v215, v121
	v_exp_f32_e32 v216, v122
	v_exp_f32_e32 v217, v123
	v_exp_f32_e32 v218, v124
	v_exp_f32_e32 v219, v125
	v_exp_f32_e32 v220, v126
	v_exp_f32_e32 v221, v127
	v_exp_f32_e32 v222, v128
	v_exp_f32_e32 v223, v129
	s_waitcnt vmcnt(0)
	s_barrier
	s_add_i32 s24, s15, s24
	v_add_u32_e32 v82, s23, v199
	ds_read_b128 v[172:175], v82 offset:57344
	ds_read_b128 v[82:85], v82 offset:49152
	v_add_u32_e32 v176, s23, v198
	s_add_u32 vcc_lo, s2, s74
	s_addc_u32 vcc_hi, s3, s75
	s_add_i32 m0, s24, 0xc000
	v_lshl_add_u64 v[250:251], v[168:169], 0, vcc
	global_load_lds_dwordx4 v[250:251], off
	v_exp_f32_e32 v177, v103
	v_exp_f32_e32 v224, v108
	v_exp_f32_e32 v225, v109
	s_waitcnt lgkmcnt(0)
	v_mfma_f32_32x32x16_bf16 v[114:129], v[82:85], v[158:161], v[66:81]
	v_exp_f32_e32 v226, v110
	v_exp_f32_e32 v227, v111
	v_exp_f32_e32 v112, v112
	v_exp_f32_e32 v113, v113
	v_mfma_f32_32x32x16_bf16 v[82:97], v[172:175], v[158:161], v[66:81]
	ds_read_b128 v[172:175], v176 offset:57344
	ds_read_b128 v[204:207], v176 offset:49152
	v_add_u32_e32 v176, s23, v197
	s_add_u32 vcc_lo, s2, 0x1c421600
	s_addc_u32 vcc_hi, s3, 0
	s_mov_b32 m0, s24
	v_lshl_add_u64 v[250:251], v[0:1], 0, vcc
	global_load_lds_dwordx4 v[250:251], off
	s_waitcnt lgkmcnt(0)
	v_mfma_f32_32x32x16_bf16 v[82:97], v[172:175], v[154:157], v[82:97]
	v_mfma_f32_32x32x16_bf16 v[114:129], v[204:207], v[154:157], v[114:129]
	ds_read_b128 v[172:175], v176 offset:57344
	ds_read_b128 v[204:207], v176 offset:49152
	v_add_u32_e32 v176, s23, v196
	s_add_u32 vcc_lo, s2, s74
	s_addc_u32 vcc_hi, s3, s75
	s_add_i32 m0, s24, 0xc400
	v_lshl_add_u64 v[250:251], v[170:171], 0, vcc
	global_load_lds_dwordx4 v[250:251], off
	s_waitcnt lgkmcnt(0)
	v_mfma_f32_32x32x16_bf16 v[82:97], v[172:175], v[150:153], v[82:97]
	v_mfma_f32_32x32x16_bf16 v[114:129], v[204:207], v[150:153], v[114:129]
	ds_read_b128 v[172:175], v176 offset:57344
	ds_read_b128 v[204:207], v176 offset:49152
	v_add_u32_e32 v176, s23, v195
	s_add_u32 vcc_lo, s2, 0x1c421680
	s_addc_u32 vcc_hi, s3, 0
	s_add_i32 m0, s24, 0x400
	v_lshl_add_u64 v[250:251], v[0:1], 0, vcc
	global_load_lds_dwordx4 v[250:251], off
	s_waitcnt lgkmcnt(0)
	v_mfma_f32_32x32x16_bf16 v[82:97], v[172:175], v[146:149], v[82:97]
	v_mfma_f32_32x32x16_bf16 v[114:129], v[204:207], v[146:149], v[114:129]
	ds_read_b128 v[172:175], v176 offset:57344
	ds_read_b128 v[204:207], v176 offset:49152
	v_add_u32_e32 v176, s23, v183
	s_waitcnt lgkmcnt(0)
	v_mfma_f32_32x32x16_bf16 v[82:97], v[172:175], v[142:145], v[82:97]
	v_mfma_f32_32x32x16_bf16 v[114:129], v[204:207], v[142:145], v[114:129]
	ds_read_b128 v[172:175], v176 offset:57344
	ds_read_b128 v[204:207], v176 offset:49152
	v_add_u32_e32 v176, s23, v193
	s_waitcnt lgkmcnt(0)
	v_mfma_f32_32x32x16_bf16 v[82:97], v[172:175], v[138:141], v[82:97]
	v_mfma_f32_32x32x16_bf16 v[114:129], v[204:207], v[138:141], v[114:129]
	ds_read_b128 v[172:175], v176 offset:57344
	ds_read_b128 v[204:207], v176 offset:49152
	v_add_u32_e32 v176, s23, v194
	s_waitcnt lgkmcnt(0)
	v_mfma_f32_32x32x16_bf16 v[82:97], v[172:175], v[134:137], v[82:97]
	v_mfma_f32_32x32x16_bf16 v[114:129], v[204:207], v[134:137], v[114:129]
	ds_read_b128 v[172:175], v176 offset:57344
	ds_read_b128 v[204:207], v176 offset:49152
	v_exp_f32_e32 v176, v102
	s_waitcnt lgkmcnt(0)
	v_mfma_f32_32x32x16_bf16 v[82:97], v[172:175], v[130:133], v[82:97]
	v_exp_f32_e32 v172, v98
	v_add_f32_e32 v98, 0, v208
	v_add_f32_e32 v98, v209, v98
	v_add_f32_e32 v98, v210, v98
	v_add_f32_e32 v98, v211, v98
	v_add_f32_e32 v98, v212, v98
	v_add_f32_e32 v98, v213, v98
	v_add_f32_e32 v98, v214, v98
	v_add_f32_e32 v98, v215, v98
	v_add_f32_e32 v98, v216, v98
	v_add_f32_e32 v98, v217, v98
	v_add_f32_e32 v98, v218, v98
	v_add_f32_e32 v98, v219, v98
	v_add_f32_e32 v98, v220, v98
	v_exp_f32_e32 v173, v99
	v_add_f32_e32 v98, v221, v98
	v_exp_f32_e32 v174, v100
	v_add_f32_e32 v98, v222, v98
	v_exp_f32_e32 v175, v101
	v_add_f32_e32 v98, v223, v98
	v_add_f32_e32 v98, v172, v98
	v_add_f32_e32 v98, v173, v98
	v_mfma_f32_32x32x16_bf16 v[114:129], v[204:207], v[130:133], v[114:129]
	v_exp_f32_e32 v204, v104
	v_add_f32_e32 v98, v174, v98
	v_exp_f32_e32 v205, v105
	v_add_f32_e32 v98, v175, v98
	v_exp_f32_e32 v206, v106
	v_add_f32_e32 v98, v176, v98
	v_exp_f32_e32 v207, v107
	v_add_f32_e32 v98, v177, v98
	v_add_f32_e32 v98, v204, v98
	v_add_f32_e32 v98, v205, v98
	v_add_f32_e32 v98, v206, v98
	v_add_f32_e32 v98, v207, v98
	v_add_f32_e32 v98, v224, v98
	v_add_f32_e32 v98, v225, v98
	v_add_f32_e32 v98, v226, v98
	v_add_f32_e32 v98, v227, v98
	v_add_f32_e32 v98, v112, v98
	v_cvt_pk_bf16_f32 v100, v208, v209
	v_cvt_pk_bf16_f32 v101, v210, v211
	v_cvt_pk_bf16_f32 v102, v212, v213
	v_cvt_pk_bf16_f32 v103, v214, v215
	v_cvt_pk_bf16_f32 v104, v216, v217
	v_cvt_pk_bf16_f32 v105, v218, v219
	v_cvt_pk_bf16_f32 v106, v220, v221
	v_cvt_pk_bf16_f32 v107, v222, v223
	v_cvt_pk_bf16_f32 v108, v172, v173
	v_cvt_pk_bf16_f32 v109, v174, v175
	v_cvt_pk_bf16_f32 v110, v176, v177
	v_cvt_pk_bf16_f32 v111, v204, v205
	v_cvt_pk_bf16_f32 v172, v206, v207
	v_cvt_pk_bf16_f32 v173, v224, v225
	v_cvt_pk_bf16_f32 v174, v226, v227
	v_cvt_pk_bf16_f32 v175, v112, v113
	v_add_u32_e32 v112, s19, v182
	ds_read_b64_tr_b16 v[204:205], v112 offset:0
	ds_read_b64_tr_b16 v[206:207], v112 offset:0x800
	ds_read_b64_tr_b16 v[208:209], v112 offset:0x1000
	ds_read_b64_tr_b16 v[210:211], v112 offset:0x1800
	ds_read_b64_tr_b16 v[212:213], v112 offset:0x2000
	ds_read_b64_tr_b16 v[214:215], v112 offset:0x2800
	ds_read_b64_tr_b16 v[216:217], v112 offset:0x3000
	ds_read_b64_tr_b16 v[218:219], v112 offset:0x3800
	v_add_f32_e32 v98, v113, v98
	s_waitcnt lgkmcnt(0)
; #define SBAR() __builtin_amdgcn_sched_barrier(0)
; __device__ __forceinline__ float max3f(float a, float b, float c) { return __builtin_fmaxf(__builtin_fmaxf(a, b), c); }
; template <bool FIRST, bool MLA>
; __device__ __forceinline__ void partialSM(f32x16& p0, f32x16& p1, f32x16& negm, float& m_reg, float& alpha) {
;   float a = max3f(p0[0], p0[1], p1[0]), b = max3f(p0[2], p0[3], p1[1]); a = max3f(a, p1[2], p1[3]);
; #pragma unroll
;   for (int r = 4; r < 16; r += 4) { a = max3f(a, p0[r], p0[r + 1]); b = max3f(b, p0[r + 2], p0[r + 3]); a = max3f(a, p1[r], p1[r + 1]); b = max3f(b, p1[r + 2], p1[r + 3]); }
;   float pmax = fmaxf(a, b);
;   { auto rr = __builtin_amdgcn_permlane32_swap(__float_as_uint(pmax), __float_as_uint(pmax), false, false);
;     pmax = fmaxf(__uint_as_float(rr[0]), __uint_as_float(rr[1])); }
;   alpha = 1.f;
;   if constexpr (MLA) {
;     if (FIRST) m_reg = pmax;
;     else if (!__builtin_expect(__all(pmax - m_reg <= THR2), 1)) { const float mn = fmaxf(m_reg, pmax); alpha = __builtin_amdgcn_exp2f(m_reg - mn); m_reg = mn; }
; #pragma unroll
;     for (int r = 0; r < 16; ++r) { p0[r] -= m_reg; p1[r] -= m_reg; }
;   } else
;   if (FIRST || __builtin_expect(__any(pmax > THR2), 0)) {
; template <int D0> __device__ __forceinline__ void pv_one(f32x16& od, int vb, bf16x8 pa0, bf16x8 pa1, bf16x8 pa2, bf16x8 pa3) {
;   const s16x4 l0 = tr_read<v_rd_off(D0, 0, 0)>(vb), h0 = tr_read<v_rd_off(D0, 0, 1)>(vb), l1 = tr_read<v_rd_off(D0, 1, 0)>(vb), h1 = tr_read<v_rd_off(D0, 1, 1)>(vb);
;   const s16x4 l2 = tr_read<v_rd_off(D0, 2, 0)>(vb), h2 = tr_read<v_rd_off(D0, 2, 1)>(vb), l3 = tr_read<v_rd_off(D0, 3, 0)>(vb), h3 = tr_read<v_rd_off(D0, 3, 1)>(vb);
;   asm volatile("s_waitcnt lgkmcnt(0)" ::: "memory"); SBAR();
;     ...
;   od = __builtin_amdgcn_mfma_f32_32x32x16_bf16(pa0, PK(l0, h0), od, 0, 0, 0);
;   od = __builtin_amdgcn_mfma_f32_32x32x16_bf16(pa1, PK(l1, h1), od, 0, 0, 0);
;   od = __builtin_amdgcn_mfma_f32_32x32x16_bf16(pa2, PK(l2, h2), od, 0, 0, 0);
;   od = __builtin_amdgcn_mfma_f32_32x32x16_bf16(pa3, PK(l3, h3), od, 0, 0, 0);
;     ...
; }
; __device__ __forceinline__ void pv_d0(f32x16* o, int vb, bf16x8 pa0, bf16x8 pa1, bf16x8 pa2, bf16x8 pa3) {
;   pv_one<0>(o[0], vb, pa0, pa1, pa2, pa3); pv_one<1>(o[1], vb, pa0, pa1, pa2, pa3); pv_one<2>(o[2], vb, pa0, pa1, pa2, pa3); pv_one<3>(o[3], vb, pa0, pa1, pa2, pa3);
	v_mov_b32_e32 v99, v98
	s_nop 1
	v_permlane32_swap_b32_e32 v98, v99
	v_permlane32_swap_b32_e32 v100, v102
	v_permlane32_swap_b32_e32 v172, v174
	v_permlane32_swap_b32_e32 v101, v103
	v_permlane32_swap_b32_e32 v104, v106
	v_permlane32_swap_b32_e32 v105, v107
	v_permlane32_swap_b32_e32 v108, v110
	v_permlane32_swap_b32_e32 v109, v111
	v_permlane32_swap_b32_e32 v173, v175
	v_mfma_f32_32x32x16_bf16 v[2:17], v[100:103], v[204:207], v[2:17]
	ds_read_b64_tr_b16 v[204:205], v112 offset:0x200
	ds_read_b64_tr_b16 v[206:207], v112 offset:0xa00
	v_mfma_f32_32x32x16_bf16 v[2:17], v[104:107], v[208:211], v[2:17]
	ds_read_b64_tr_b16 v[208:209], v112 offset:0x1200
	ds_read_b64_tr_b16 v[210:211], v112 offset:0x1a00
	v_mfma_f32_32x32x16_bf16 v[2:17], v[108:111], v[212:215], v[2:17]
	ds_read_b64_tr_b16 v[212:213], v112 offset:0x2200
	ds_read_b64_tr_b16 v[214:215], v112 offset:0x2a00
	v_mfma_f32_32x32x16_bf16 v[2:17], v[172:175], v[216:219], v[2:17]
	ds_read_b64_tr_b16 v[216:217], v112 offset:0x3200
	ds_read_b64_tr_b16 v[218:219], v112 offset:0x3a00
	s_waitcnt lgkmcnt(6)
	v_mfma_f32_32x32x16_bf16 v[50:65], v[100:103], v[204:207], v[50:65]
	ds_read_b64_tr_b16 v[204:205], v112 offset:0x400
	ds_read_b64_tr_b16 v[206:207], v112 offset:0xc00
	s_waitcnt lgkmcnt(6)
	v_mfma_f32_32x32x16_bf16 v[50:65], v[104:107], v[208:211], v[50:65]
	ds_read_b64_tr_b16 v[208:209], v112 offset:0x1400
	ds_read_b64_tr_b16 v[210:211], v112 offset:0x1c00
	s_waitcnt lgkmcnt(6)
	v_mfma_f32_32x32x16_bf16 v[50:65], v[108:111], v[212:215], v[50:65]
	ds_read_b64_tr_b16 v[212:213], v112 offset:0x2400
	ds_read_b64_tr_b16 v[214:215], v112 offset:0x2c00
	s_waitcnt lgkmcnt(6)
	v_mfma_f32_32x32x16_bf16 v[50:65], v[172:175], v[216:219], v[50:65]
	ds_read_b64_tr_b16 v[216:217], v112 offset:0x3400
	ds_read_b64_tr_b16 v[218:219], v112 offset:0x3c00
	s_waitcnt lgkmcnt(6)
	v_mfma_f32_32x32x16_bf16 v[34:49], v[100:103], v[204:207], v[34:49]
	ds_read_b64_tr_b16 v[204:205], v112 offset:0x600
	ds_read_b64_tr_b16 v[206:207], v112 offset:0xe00
	s_waitcnt lgkmcnt(6)
	v_mfma_f32_32x32x16_bf16 v[34:49], v[104:107], v[208:211], v[34:49]
	ds_read_b64_tr_b16 v[208:209], v112 offset:0x1600
	ds_read_b64_tr_b16 v[210:211], v112 offset:0x1e00
	s_waitcnt lgkmcnt(6)
	v_mfma_f32_32x32x16_bf16 v[34:49], v[108:111], v[212:215], v[34:49]
	ds_read_b64_tr_b16 v[212:213], v112 offset:0x2600
	ds_read_b64_tr_b16 v[214:215], v112 offset:0x2e00
	s_waitcnt lgkmcnt(6)
	v_mfma_f32_32x32x16_bf16 v[34:49], v[172:175], v[216:219], v[34:49]
	ds_read_b64_tr_b16 v[216:217], v112 offset:0x3600
	ds_read_b64_tr_b16 v[218:219], v112 offset:0x3e00
	s_waitcnt lgkmcnt(6)
	v_mfma_f32_32x32x16_bf16 v[18:33], v[100:103], v[204:207], v[18:33]
	v_max_f32_e32 v100, v115, v115
	v_max_f32_e32 v101, v114, v114
	v_max_f32_e32 v100, v101, v100
	v_max3_f32 v101, v116, v117, v83
	v_max3_f32 v100, v100, v82, v84
	v_max3_f32 v100, v100, v85, v118
	v_max3_f32 v101, v101, v120, v121
	s_waitcnt lgkmcnt(4)
	v_mfma_f32_32x32x16_bf16 v[18:33], v[104:107], v[208:211], v[18:33]
	v_max3_f32 v100, v100, v119, v86
	v_max3_f32 v101, v101, v88, v89
	v_max3_f32 v100, v100, v87, v122
	v_max3_f32 v101, v101, v124, v125
	v_max3_f32 v100, v100, v123, v90
	v_max3_f32 v101, v101, v92, v93
	v_max3_f32 v100, v100, v91, v126
	s_waitcnt lgkmcnt(2)
	v_mfma_f32_32x32x16_bf16 v[18:33], v[108:111], v[212:215], v[18:33]
	v_max3_f32 v101, v101, v128, v129
	v_max3_f32 v100, v100, v127, v94
	v_max3_f32 v101, v101, v96, v97
	v_max3_f32 v100, v100, v95, v101
	v_mov_b32_e32 v101, v100
	s_nop 1
	v_permlane32_swap_b32_e32 v100, v101
	s_waitcnt lgkmcnt(0)
	v_mfma_f32_32x32x16_bf16 v[18:33], v[172:175], v[216:219], v[18:33]
	v_max_f32_e32 v101, v101, v101
	v_max_f32_e32 v100, v100, v100
	v_max_f32_e32 v100, v100, v101
	v_cmp_lt_f32_e32 vcc, s40, v100
	v_mov_b32_e32 v172, 1.0
	s_cbranch_vccnz .LBB0_138
	s_branch .LBB0_135

; __device__ __forceinline__ void finishSM(f32x16& p0, f32x16& p1, float alpha, float& l_reg, bf16x8& pa0, bf16x8& pa1, bf16x8& pa2, bf16x8& pa3) {
; #pragma unroll
;   for (int r = 0; r < 16; ++r) p1[r] = __builtin_amdgcn_exp2f(p1[r]);
;   float ps = 0;
; #pragma unroll
;   for (int r = 0; r < 16; ++r) ps += p0[r];
; #pragma unroll
;   for (int r = 0; r < 16; ++r) ps += p1[r];
;   { auto rr = __builtin_amdgcn_permlane32_swap(__float_as_uint(ps), __float_as_uint(ps), false, false);
;     ps = __uint_as_float(rr[0]) + __uint_as_float(rr[1]); }
;   l_reg = l_reg * alpha + ps;
;     ...
;   PK4(p0, 0, pa0); PK4(p0, 8, pa1); PK4(p1, 0, pa2); PK4(p1, 8, pa3);
; template <bool MLA>
; __device__ __forceinline__ void qkt(f32x16& p0, f32x16& p1, const char* Ks, const char* KRs, const bf16x8* qr, const char* qrl, const f32x16& negm, int r32, int hi) {
; #pragma unroll
;   for (int d0 = 0; d0 < 8; ++d0) { int cb = (d0 * 16 + hi * 8) * 2;
;     bf16x8 b0 = *reinterpret_cast<const bf16x8*>(Ks + KSWZ(r32, cb));
;     bf16x8 b1 = *reinterpret_cast<const bf16x8*>(Ks + KSWZ(32 + r32, cb));
;     if (d0 == 0) { p0 = __builtin_amdgcn_mfma_f32_32x32x16_bf16(b0, qr[0], negm, 0, 0, 0); p1 = __builtin_amdgcn_mfma_f32_32x32x16_bf16(b1, qr[0], negm, 0, 0, 0); }
;     else { p0 = __builtin_amdgcn_mfma_f32_32x32x16_bf16(b0, qr[d0], p0, 0, 0, 0); p1 = __builtin_amdgcn_mfma_f32_32x32x16_bf16(b1, qr[d0], p1, 0, 0, 0); } }
.LBB0_139:
	s_add_i32 s2, 0, 0x10000
	v_add_u32_e32 v0, s2, v199
	ds_read_b128 v[168:171], v0 offset:8192
	ds_read_b128 v[98:101], v0
	v_add_u32_e32 v0, s2, v198
	v_exp_f32_e32 v83, v83
	v_exp_f32_e32 v96, v96
	v_exp_f32_e32 v97, v97
	s_waitcnt lgkmcnt(0)
	v_mfma_f32_32x32x16_bf16 v[114:129], v[98:101], v[158:161], v[66:81]
	v_mfma_f32_32x32x16_bf16 v[98:113], v[168:171], v[158:161], v[66:81]
	ds_read_b128 v[158:161], v0 offset:8192
	ds_read_b128 v[168:171], v0
	v_add_u32_e32 v0, s2, v197
	s_waitcnt lgkmcnt(0)
	v_mfma_f32_32x32x16_bf16 v[114:129], v[168:171], v[154:157], v[114:129]
	v_mfma_f32_32x32x16_bf16 v[98:113], v[158:161], v[154:157], v[98:113]
	ds_read_b128 v[154:157], v0 offset:8192
	ds_read_b128 v[158:161], v0
	v_add_u32_e32 v0, s2, v196
	s_waitcnt lgkmcnt(0)
	v_mfma_f32_32x32x16_bf16 v[114:129], v[158:161], v[150:153], v[114:129]
	v_mfma_f32_32x32x16_bf16 v[98:113], v[154:157], v[150:153], v[98:113]
	ds_read_b128 v[150:153], v0 offset:8192
	ds_read_b128 v[154:157], v0
	v_add_u32_e32 v0, s2, v195
	s_waitcnt lgkmcnt(0)
	v_mfma_f32_32x32x16_bf16 v[114:129], v[154:157], v[146:149], v[114:129]
	v_mfma_f32_32x32x16_bf16 v[98:113], v[150:153], v[146:149], v[98:113]
	ds_read_b128 v[146:149], v0 offset:8192
	ds_read_b128 v[150:153], v0
	v_add_u32_e32 v0, s2, v183
	s_waitcnt lgkmcnt(0)
	v_mfma_f32_32x32x16_bf16 v[114:129], v[150:153], v[142:145], v[114:129]
	v_mfma_f32_32x32x16_bf16 v[98:113], v[146:149], v[142:145], v[98:113]
	ds_read_b128 v[142:145], v0 offset:8192
	ds_read_b128 v[146:149], v0
	v_add_u32_e32 v0, s2, v193
	s_waitcnt lgkmcnt(0)
	v_mfma_f32_32x32x16_bf16 v[114:129], v[146:149], v[138:141], v[114:129]
	v_mfma_f32_32x32x16_bf16 v[98:113], v[142:145], v[138:141], v[98:113]
	ds_read_b128 v[138:141], v0 offset:8192
	ds_read_b128 v[142:145], v0
	v_add_u32_e32 v0, s2, v194
	s_waitcnt lgkmcnt(0)
	v_mfma_f32_32x32x16_bf16 v[114:129], v[142:145], v[134:137], v[114:129]
	v_exp_f32_e32 v142, v95
	v_mfma_f32_32x32x16_bf16 v[98:113], v[138:141], v[134:137], v[98:113]
	ds_read_b128 v[134:137], v0 offset:8192
	ds_read_b128 v[138:141], v0
	v_add_f32_e32 v0, 0, v217
	v_add_f32_e32 v0, v219, v0
	v_add_f32_e32 v0, v215, v0
	v_add_f32_e32 v0, v218, v0
	v_add_f32_e32 v0, v214, v0
	v_add_f32_e32 v0, v216, v0
	v_add_f32_e32 v0, v212, v0
	v_add_f32_e32 v0, v213, v0
	v_add_f32_e32 v0, v209, v0
	v_add_f32_e32 v0, v211, v0
	v_add_f32_e32 v0, v208, v0
	v_add_f32_e32 v0, v210, v0
	s_waitcnt lgkmcnt(0)
	v_mfma_f32_32x32x16_bf16 v[114:129], v[138:141], v[130:133], v[114:129]
	v_add_f32_e32 v0, v205, v0
	v_add_f32_e32 v0, v207, v0
	v_add_f32_e32 v0, v204, v0
	v_add_f32_e32 v0, v206, v0
	v_exp_f32_e32 v138, v91
	v_exp_f32_e32 v139, v92
	v_exp_f32_e32 v140, v93
	v_mfma_f32_32x32x16_bf16 v[98:113], v[134:137], v[130:133], v[98:113]
	v_exp_f32_e32 v130, v82
	v_exp_f32_e32 v131, v84
	v_exp_f32_e32 v132, v85
	v_exp_f32_e32 v133, v86
	v_add_f32_e32 v0, v130, v0
	v_exp_f32_e32 v134, v87
	v_add_f32_e32 v0, v83, v0
	v_exp_f32_e32 v135, v88
	v_add_f32_e32 v0, v131, v0
	v_exp_f32_e32 v136, v89
	v_add_f32_e32 v0, v132, v0
	v_exp_f32_e32 v137, v90
	v_add_f32_e32 v0, v133, v0
	v_add_f32_e32 v0, v134, v0
	v_add_f32_e32 v0, v135, v0
	v_add_f32_e32 v0, v136, v0
	v_exp_f32_e32 v141, v94
	v_add_f32_e32 v0, v137, v0
	v_add_f32_e32 v0, v138, v0
	v_add_f32_e32 v0, v139, v0
	v_add_f32_e32 v0, v140, v0
	v_add_f32_e32 v0, v141, v0
	v_add_f32_e32 v0, v142, v0
	v_add_f32_e32 v0, v96, v0
	v_add_f32_e32 v0, v97, v0
	v_mov_b32_e32 v82, v0
	v_cvt_pk_bf16_f32 v84, v217, v219
	v_cvt_pk_bf16_f32 v85, v215, v218
	v_cvt_pk_bf16_f32 v86, v214, v216
	s_nop 1
	v_permlane32_swap_b32_e32 v0, v82
	v_cvt_pk_bf16_f32 v87, v212, v213
	v_permlane32_swap_b32_e32 v84, v86
	v_cvt_pk_bf16_f32 v88, v209, v211
	v_cvt_pk_bf16_f32 v89, v208, v210
	v_cvt_pk_bf16_f32 v90, v205, v207
	v_cvt_pk_bf16_f32 v91, v204, v206
	v_cvt_pk_bf16_f32 v92, v130, v83
	v_cvt_pk_bf16_f32 v93, v131, v132
	v_cvt_pk_bf16_f32 v94, v133, v134
	v_cvt_pk_bf16_f32 v95, v135, v136
	v_cvt_pk_bf16_f32 v130, v137, v138
	v_cvt_pk_bf16_f32 v131, v139, v140
	v_cvt_pk_bf16_f32 v132, v141, v142
	v_cvt_pk_bf16_f32 v133, v96, v97
	v_permlane32_swap_b32_e32 v85, v87
	v_permlane32_swap_b32_e32 v88, v90
	v_permlane32_swap_b32_e32 v89, v91
	v_permlane32_swap_b32_e32 v92, v94
	v_permlane32_swap_b32_e32 v93, v95
	v_permlane32_swap_b32_e32 v130, v132
	v_permlane32_swap_b32_e32 v131, v133
	ds_read_b64_tr_b16 v[134:135], v182 offset:0
	ds_read_b64_tr_b16 v[136:137], v182 offset:0x800
	ds_read_b64_tr_b16 v[138:139], v182 offset:0x1000
	ds_read_b64_tr_b16 v[140:141], v182 offset:0x1800
	ds_read_b64_tr_b16 v[142:143], v182 offset:0x2000
	ds_read_b64_tr_b16 v[144:145], v182 offset:0x2800
	ds_read_b64_tr_b16 v[146:147], v182 offset:0x3000
	ds_read_b64_tr_b16 v[148:149], v182 offset:0x3800
	s_waitcnt lgkmcnt(0)
; #define SBAR() __builtin_amdgcn_sched_barrier(0)
; __device__ __forceinline__ float max3f(float a, float b, float c) { return __builtin_fmaxf(__builtin_fmaxf(a, b), c); }
; template <bool FIRST, bool MLA>
; __device__ __forceinline__ void partialSM(f32x16& p0, f32x16& p1, f32x16& negm, float& m_reg, float& alpha) {
;   float a = max3f(p0[0], p0[1], p1[0]), b = max3f(p0[2], p0[3], p1[1]); a = max3f(a, p1[2], p1[3]);
; #pragma unroll
;   for (int r = 4; r < 16; r += 4) { a = max3f(a, p0[r], p0[r + 1]); b = max3f(b, p0[r + 2], p0[r + 3]); a = max3f(a, p1[r], p1[r + 1]); b = max3f(b, p1[r + 2], p1[r + 3]); }
;   float pmax = fmaxf(a, b);
;   { auto rr = __builtin_amdgcn_permlane32_swap(__float_as_uint(pmax), __float_as_uint(pmax), false, false);
;     pmax = fmaxf(__uint_as_float(rr[0]), __uint_as_float(rr[1])); }
;   alpha = 1.f;
;   if constexpr (MLA) {
;     if (FIRST) m_reg = pmax;
;     else if (!__builtin_expect(__all(pmax - m_reg <= THR2), 1)) { const float mn = fmaxf(m_reg, pmax); alpha = __builtin_amdgcn_exp2f(m_reg - mn); m_reg = mn; }
; #pragma unroll
;     for (int r = 0; r < 16; ++r) { p0[r] -= m_reg; p1[r] -= m_reg; }
;   } else
;   if (FIRST || __builtin_expect(__any(pmax > THR2), 0)) {
; template <int D0> __device__ __forceinline__ void pv_one(f32x16& od, int vb, bf16x8 pa0, bf16x8 pa1, bf16x8 pa2, bf16x8 pa3) {
;   const s16x4 l0 = tr_read<v_rd_off(D0, 0, 0)>(vb), h0 = tr_read<v_rd_off(D0, 0, 1)>(vb), l1 = tr_read<v_rd_off(D0, 1, 0)>(vb), h1 = tr_read<v_rd_off(D0, 1, 1)>(vb);
;   const s16x4 l2 = tr_read<v_rd_off(D0, 2, 0)>(vb), h2 = tr_read<v_rd_off(D0, 2, 1)>(vb), l3 = tr_read<v_rd_off(D0, 3, 0)>(vb), h3 = tr_read<v_rd_off(D0, 3, 1)>(vb);
;   asm volatile("s_waitcnt lgkmcnt(0)" ::: "memory"); SBAR();
;     ...
;   od = __builtin_amdgcn_mfma_f32_32x32x16_bf16(pa0, PK(l0, h0), od, 0, 0, 0);
;   od = __builtin_amdgcn_mfma_f32_32x32x16_bf16(pa1, PK(l1, h1), od, 0, 0, 0);
;   od = __builtin_amdgcn_mfma_f32_32x32x16_bf16(pa2, PK(l2, h2), od, 0, 0, 0);
;   od = __builtin_amdgcn_mfma_f32_32x32x16_bf16(pa3, PK(l3, h3), od, 0, 0, 0);
;     ...
; }
; __device__ __forceinline__ void pv_d0(f32x16* o, int vb, bf16x8 pa0, bf16x8 pa1, bf16x8 pa2, bf16x8 pa3) {
;   pv_one<0>(o[0], vb, pa0, pa1, pa2, pa3); pv_one<1>(o[1], vb, pa0, pa1, pa2, pa3); pv_one<2>(o[2], vb, pa0, pa1, pa2, pa3); pv_one<3>(o[3], vb, pa0, pa1, pa2, pa3);
	s_nop 0
	v_mfma_f32_32x32x16_bf16 v[2:17], v[84:87], v[134:137], v[2:17]
	ds_read_b64_tr_b16 v[134:135], v182 offset:0x200
	ds_read_b64_tr_b16 v[136:137], v182 offset:0xa00
	v_mfma_f32_32x32x16_bf16 v[2:17], v[88:91], v[138:141], v[2:17]
	ds_read_b64_tr_b16 v[138:139], v182 offset:0x1200
	ds_read_b64_tr_b16 v[140:141], v182 offset:0x1a00
	v_mfma_f32_32x32x16_bf16 v[2:17], v[92:95], v[142:145], v[2:17]
	ds_read_b64_tr_b16 v[142:143], v182 offset:0x2200
	ds_read_b64_tr_b16 v[144:145], v182 offset:0x2a00
	v_mfma_f32_32x32x16_bf16 v[2:17], v[130:133], v[146:149], v[2:17]
	ds_read_b64_tr_b16 v[146:147], v182 offset:0x3200
	ds_read_b64_tr_b16 v[148:149], v182 offset:0x3a00
	s_waitcnt lgkmcnt(0)
	v_mfma_f32_32x32x16_bf16 v[50:65], v[84:87], v[134:137], v[50:65]
	ds_read_b64_tr_b16 v[134:135], v182 offset:0x400
	ds_read_b64_tr_b16 v[136:137], v182 offset:0xc00
	v_mfma_f32_32x32x16_bf16 v[50:65], v[88:91], v[138:141], v[50:65]
	ds_read_b64_tr_b16 v[138:139], v182 offset:0x1400
	ds_read_b64_tr_b16 v[140:141], v182 offset:0x1c00
	v_mfma_f32_32x32x16_bf16 v[50:65], v[92:95], v[142:145], v[50:65]
	ds_read_b64_tr_b16 v[142:143], v182 offset:0x2400
	ds_read_b64_tr_b16 v[144:145], v182 offset:0x2c00
	v_mfma_f32_32x32x16_bf16 v[50:65], v[130:133], v[146:149], v[50:65]
	ds_read_b64_tr_b16 v[146:147], v182 offset:0x3400
	ds_read_b64_tr_b16 v[148:149], v182 offset:0x3c00
	s_waitcnt lgkmcnt(0)
	v_mfma_f32_32x32x16_bf16 v[34:49], v[84:87], v[134:137], v[34:49]
	ds_read_b64_tr_b16 v[134:135], v182 offset:0x600
	ds_read_b64_tr_b16 v[136:137], v182 offset:0xe00
	v_mfma_f32_32x32x16_bf16 v[34:49], v[88:91], v[138:141], v[34:49]
	ds_read_b64_tr_b16 v[138:139], v182 offset:0x1600
	ds_read_b64_tr_b16 v[140:141], v182 offset:0x1e00
	v_mfma_f32_32x32x16_bf16 v[34:49], v[92:95], v[142:145], v[34:49]
	ds_read_b64_tr_b16 v[142:143], v182 offset:0x2600
	ds_read_b64_tr_b16 v[144:145], v182 offset:0x2e00
	v_mfma_f32_32x32x16_bf16 v[34:49], v[130:133], v[146:149], v[34:49]
	ds_read_b64_tr_b16 v[146:147], v182 offset:0x3600
	ds_read_b64_tr_b16 v[148:149], v182 offset:0x3e00
	s_waitcnt lgkmcnt(0)
	v_mfma_f32_32x32x16_bf16 v[18:33], v[84:87], v[134:137], v[18:33]
	v_max_f32_e32 v83, v115, v115
	v_max_f32_e32 v84, v114, v114
	v_max_f32_e32 v83, v84, v83
	v_max3_f32 v84, v116, v117, v99
	v_max3_f32 v83, v83, v98, v100
	v_max3_f32 v83, v83, v101, v118
	v_max3_f32 v84, v84, v120, v121
	v_mfma_f32_32x32x16_bf16 v[18:33], v[88:91], v[138:141], v[18:33]
	v_max3_f32 v83, v83, v119, v102
	v_max3_f32 v84, v84, v104, v105
	v_max3_f32 v83, v83, v103, v122
	v_max3_f32 v84, v84, v124, v125
	v_max3_f32 v83, v83, v123, v106
	v_max3_f32 v84, v84, v108, v109
	v_max3_f32 v83, v83, v107, v126
	v_mfma_f32_32x32x16_bf16 v[18:33], v[92:95], v[142:145], v[18:33]
	v_max3_f32 v84, v84, v128, v129
	v_max3_f32 v83, v83, v127, v110
	v_max3_f32 v84, v84, v112, v113
	v_max3_f32 v83, v83, v111, v84
	v_mov_b32_e32 v84, v83
	s_nop 1
	v_permlane32_swap_b32_e32 v83, v84
	v_mfma_f32_32x32x16_bf16 v[18:33], v[130:133], v[146:149], v[18:33]
	v_max_f32_e32 v84, v84, v84
	v_max_f32_e32 v83, v83, v83
	v_max_f32_e32 v84, v83, v84
	v_cmp_lt_f32_e32 vcc, s40, v84
	v_mov_b32_e32 v83, 1.0
	s_cbranch_vccnz .LBB0_147
	s_branch .LBB0_144
